# GEMM K-loop LDS-DMA via scalar base + 32-bit lane offset (64-bit VALU adds replaced by s_nop 0, wait states preserved)
# speedup vs baseline: 1.0129x; 1.0064x over previous
.LBB0_80:
	s_add_u32 s6, s6, 0xa900000
	s_addc_u32 s7, s7, 0
	s_lshl_b32 s12, s12, 5
	s_and_b32 s17, s12, 0x60
	s_mov_b64 s[12:13], 0x80
	s_add_i32 m0, s27, 0x18000
	v_lshl_add_u64 v[8:9], v[8:9], 0, s[12:13]
	s_lshl_b32 s16, s3, 13
	s_lshl_b32 s18, s17, 7
	s_waitcnt vmcnt(2)
	s_barrier
	global_load_lds_dwordx4 v[8:9], off
	v_lshl_add_u64 v[6:7], v[6:7], 0, s[12:13]
	s_add_i32 m0, s27, 0x1a000
	s_add_i32 s45, s27, 0x8000
	s_add_i32 s46, s27, 0xa000
	global_load_lds_dwordx4 v[6:7], off
	v_lshl_add_u64 v[2:3], v[2:3], 0, s[12:13]
	s_mov_b32 m0, s45
	s_add_u32 s14, s30, 0x40080
	global_load_lds_dwordx4 v[2:3], off
	v_lshl_add_u64 v[2:3], v[4:5], 0, s[12:13]
	s_mov_b32 m0, s46
	s_addc_u32 s15, s31, 0
	global_load_lds_dwordx4 v[2:3], off
	s_add_i32 m0, s27, 0x1c000
	s_nop 0
	global_load_lds_dwordx4 v134, s[14:15]
	s_nop 0
	s_add_i32 m0, s27, 0x1e000
	s_sext_i32_i8 s51, s2
	global_load_lds_dwordx4 v130, s[14:15]
	v_and_b32_e32 v2, 15, v10
	v_lshlrev_b32_e32 v3, 1, v14
	v_lshlrev_b32_e32 v4, 2, v10
	v_lshlrev_b32_e32 v5, 6, v10
	s_movk_i32 s2, 0x3c0
	v_lshl_or_b32 v1, s3, 6, v2
	v_lshl_or_b32 v2, v2, 6, v3
	v_and_b32_e32 v4, 32, v4
	v_and_or_b32 v3, v5, s2, v3
	v_bitop3_b32 v148, s18, v3, v4 bitop3:0xf6
	v_lshlrev_b32_e32 v3, 8, v10
	v_bitop3_b32 v2, v2, s16, v4 bitop3:0xde
	v_and_b32_e32 v3, 0x38000, v3
	v_lshlrev_b32_e32 v4, 11, v15
	v_or3_b32 v3, v12, v3, v4
	v_add_u32_e32 v138, v3, v13
	v_lshlrev_b32_e32 v3, 4, v11
	s_waitcnt vmcnt(6)
	s_cmpk_lt_u32 s10, 0x100
	v_and_b32_e32 v3, 0x78000, v3
	s_cselect_b64 s[14:15], -1, 0
	v_or3_b32 v3, v12, v3, v4
	s_add_i32 s48, 0, 0x10000
	s_add_i32 s49, 0, 0x14000
	s_ashr_i32 s47, s11, 31
	v_or_b32_e32 v149, s17, v14
	v_mov_b32_e32 v139, v135
	v_add_u32_e32 v140, v3, v13
	v_mov_b32_e32 v141, v135
	v_mov_b64_e32 v[142:143], 0xb00
	v_mov_b64_e32 v[144:145], 0xaff
	v_add_u32_e32 v150, s48, v148
	v_add_u32_e32 v151, s49, v148
	v_add_u32_e32 v152, 0, v2
	s_movk_i32 s50, 0x1600
	s_barrier
	s_branch .LBB0_83

.LBB0_86:
	ds_read_b128 v[154:157], v150
	ds_read_b128 v[158:161], v150 offset:1024
	ds_read_b128 v[162:165], v150 offset:2048
	ds_read_b128 v[166:169], v150 offset:3072
	ds_read_b128 v[170:173], v151
	ds_read_b128 v[174:177], v151 offset:1024
	ds_read_b128 v[178:181], v151 offset:2048
	ds_read_b128 v[182:185], v151 offset:3072
	s_add_u32 s30, s28, 0xfffc0080
	s_addc_u32 s31, s29, -1
	s_cmp_eq_u32 s53, 12
	s_cselect_b32 s35, s10, s31
	s_cselect_b32 s34, s19, s30
	s_cselect_b32 s31, s17, s52
	s_cselect_b32 s30, s20, s21
	s_nop 0
	s_add_i32 m0, s27, 0xc000
	ds_read_b128 v[186:189], v152
	ds_read_b128 v[190:193], v152 offset:1024
	ds_read_b128 v[194:197], v152 offset:2048
	ds_read_b128 v[198:201], v152 offset:3072
	ds_read_b128 v[202:205], v152 offset:4096
	ds_read_b128 v[206:209], v152 offset:5120
	ds_read_b128 v[210:213], v152 offset:6144
	ds_read_b128 v[214:217], v152 offset:7168
	global_load_lds_dwordx4 v138, s[28:29]
	s_nop 0
	s_add_i32 m0, s27, 0xe000
	s_nop 0
	global_load_lds_dwordx4 v140, s[28:29]
	s_waitcnt vmcnt(8)
	s_waitcnt lgkmcnt(0)
	s_barrier
	s_setprio 1
	s_waitcnt lgkmcnt(0)
	v_mfma_f32_16x16x32_bf16 v[126:129], v[154:157], v[186:189], v[126:129]
	v_mfma_f32_16x16x32_bf16 v[122:125], v[162:165], v[186:189], v[122:125]
	v_mfma_f32_16x16x32_bf16 v[110:113], v[154:157], v[194:197], v[110:113]
	v_mfma_f32_16x16x32_bf16 v[106:109], v[162:165], v[194:197], v[106:109]
	v_mfma_f32_16x16x32_bf16 v[94:97], v[154:157], v[202:205], v[94:97]
	v_mfma_f32_16x16x32_bf16 v[90:93], v[162:165], v[202:205], v[90:93]
	v_mfma_f32_16x16x32_bf16 v[78:81], v[154:157], v[210:213], v[78:81]
	v_mfma_f32_16x16x32_bf16 v[74:77], v[162:165], v[210:213], v[74:77]
	v_mfma_f32_16x16x32_bf16 v[126:129], v[158:161], v[190:193], v[126:129]
	v_mfma_f32_16x16x32_bf16 v[122:125], v[166:169], v[190:193], v[122:125]
	v_mfma_f32_16x16x32_bf16 v[110:113], v[158:161], v[198:201], v[110:113]
	v_mfma_f32_16x16x32_bf16 v[106:109], v[166:169], v[198:201], v[106:109]
	v_mfma_f32_16x16x32_bf16 v[94:97], v[158:161], v[206:209], v[94:97]
	v_mfma_f32_16x16x32_bf16 v[90:93], v[166:169], v[206:209], v[90:93]
	v_mfma_f32_16x16x32_bf16 v[78:81], v[158:161], v[214:217], v[78:81]
	v_mfma_f32_16x16x32_bf16 v[74:77], v[166:169], v[214:217], v[74:77]
	s_setprio 0
	s_setprio 1
	v_mfma_f32_16x16x32_bf16 v[118:121], v[170:173], v[186:189], v[118:121]
	v_mfma_f32_16x16x32_bf16 v[114:117], v[178:181], v[186:189], v[114:117]
	v_mfma_f32_16x16x32_bf16 v[102:105], v[170:173], v[194:197], v[102:105]
	v_mfma_f32_16x16x32_bf16 v[98:101], v[178:181], v[194:197], v[98:101]
	v_mfma_f32_16x16x32_bf16 v[86:89], v[170:173], v[202:205], v[86:89]
	v_mfma_f32_16x16x32_bf16 v[82:85], v[178:181], v[202:205], v[82:85]
	v_mfma_f32_16x16x32_bf16 v[70:73], v[170:173], v[210:213], v[70:73]
	v_mfma_f32_16x16x32_bf16 v[66:69], v[178:181], v[210:213], v[66:69]
	v_mfma_f32_16x16x32_bf16 v[118:121], v[174:177], v[190:193], v[118:121]
	v_mfma_f32_16x16x32_bf16 v[114:117], v[182:185], v[190:193], v[114:117]
	v_mfma_f32_16x16x32_bf16 v[102:105], v[174:177], v[198:201], v[102:105]
	v_mfma_f32_16x16x32_bf16 v[98:101], v[182:185], v[198:201], v[98:101]
	v_mfma_f32_16x16x32_bf16 v[86:89], v[174:177], v[206:209], v[86:89]
	v_mfma_f32_16x16x32_bf16 v[82:85], v[182:185], v[206:209], v[82:85]
	v_mfma_f32_16x16x32_bf16 v[70:73], v[174:177], v[214:217], v[70:73]
	v_mfma_f32_16x16x32_bf16 v[66:69], v[182:185], v[214:217], v[66:69]
	s_setprio 0
	s_barrier
	s_add_i32 s54, s48, s38
	v_lshl_add_u64 v[146:147], s[30:31], 0, v[134:135]
	s_mov_b32 m0, s54
	ds_read_b128 v[186:189], v152 offset:16384
	ds_read_b128 v[190:193], v152 offset:17408
	ds_read_b128 v[194:197], v152 offset:18432
	ds_read_b128 v[198:201], v152 offset:19456
	ds_read_b128 v[202:205], v152 offset:20480
	ds_read_b128 v[206:209], v152 offset:21504
	ds_read_b128 v[210:213], v152 offset:22528
	ds_read_b128 v[214:217], v152 offset:23552
	global_load_lds_dwordx4 v[146:147], off
	s_add_i32 m0, s54, 0x2000
	s_add_u32 s54, s30, 0x40000
	v_lshl_add_u64 v[218:219], s[30:31], 0, v[130:131]
	s_addc_u32 s55, s31, 0
	s_add_i32 s56, s49, s38
	global_load_lds_dwordx4 v[218:219], off
	s_nop 0
	s_mov_b32 m0, s56
	v_lshl_add_u64 v[222:223], s[34:35], 0, v[132:133]
	global_load_lds_dwordx4 v134, s[54:55]
	s_nop 0
	s_add_i32 m0, s56, 0x2000
	s_nop 0
	global_load_lds_dwordx4 v130, s[54:55]
	v_lshl_add_u64 v[220:221], s[34:35], 0, v[136:137]
	s_mov_b32 m0, s27
	s_nop 0
	global_load_lds_dwordx4 v[220:221], off
	s_mov_b32 m0, s41
	s_nop 0
	global_load_lds_dwordx4 v[222:223], off
	s_waitcnt vmcnt(8)
	s_waitcnt lgkmcnt(0)
	s_barrier
	s_setprio 1
	s_waitcnt lgkmcnt(0)
	v_mfma_f32_16x16x32_bf16 v[62:65], v[154:157], v[186:189], v[62:65]
	v_mfma_f32_16x16x32_bf16 v[58:61], v[162:165], v[186:189], v[58:61]
	v_mfma_f32_16x16x32_bf16 v[46:49], v[154:157], v[194:197], v[46:49]
	v_mfma_f32_16x16x32_bf16 v[42:45], v[162:165], v[194:197], v[42:45]
	v_mfma_f32_16x16x32_bf16 v[30:33], v[154:157], v[202:205], v[30:33]
	v_mfma_f32_16x16x32_bf16 v[26:29], v[162:165], v[202:205], v[26:29]
	v_mfma_f32_16x16x32_bf16 v[14:17], v[154:157], v[210:213], v[14:17]
	v_mfma_f32_16x16x32_bf16 v[10:13], v[162:165], v[210:213], v[10:13]
	v_mfma_f32_16x16x32_bf16 v[62:65], v[158:161], v[190:193], v[62:65]
	v_mfma_f32_16x16x32_bf16 v[58:61], v[166:169], v[190:193], v[58:61]
	v_mfma_f32_16x16x32_bf16 v[46:49], v[158:161], v[198:201], v[46:49]
	v_mfma_f32_16x16x32_bf16 v[42:45], v[166:169], v[198:201], v[42:45]
	v_mfma_f32_16x16x32_bf16 v[30:33], v[158:161], v[206:209], v[30:33]
	v_mfma_f32_16x16x32_bf16 v[26:29], v[166:169], v[206:209], v[26:29]
	v_mfma_f32_16x16x32_bf16 v[14:17], v[158:161], v[214:217], v[14:17]
	v_mfma_f32_16x16x32_bf16 v[10:13], v[166:169], v[214:217], v[10:13]
	s_setprio 0
	s_setprio 1
	v_mfma_f32_16x16x32_bf16 v[54:57], v[170:173], v[186:189], v[54:57]
	v_mfma_f32_16x16x32_bf16 v[50:53], v[178:181], v[186:189], v[50:53]
	v_mfma_f32_16x16x32_bf16 v[38:41], v[170:173], v[194:197], v[38:41]
	v_mfma_f32_16x16x32_bf16 v[34:37], v[178:181], v[194:197], v[34:37]
	v_mfma_f32_16x16x32_bf16 v[22:25], v[170:173], v[202:205], v[22:25]
	v_mfma_f32_16x16x32_bf16 v[18:21], v[178:181], v[202:205], v[18:21]
	v_mfma_f32_16x16x32_bf16 v[6:9], v[170:173], v[210:213], v[6:9]
	v_mfma_f32_16x16x32_bf16 v[2:5], v[178:181], v[210:213], v[2:5]
	v_mfma_f32_16x16x32_bf16 v[54:57], v[174:177], v[190:193], v[54:57]
	v_mfma_f32_16x16x32_bf16 v[50:53], v[182:185], v[190:193], v[50:53]
	v_mfma_f32_16x16x32_bf16 v[38:41], v[174:177], v[198:201], v[38:41]
	v_mfma_f32_16x16x32_bf16 v[34:37], v[182:185], v[198:201], v[34:37]
	v_mfma_f32_16x16x32_bf16 v[22:25], v[174:177], v[206:209], v[22:25]
	v_mfma_f32_16x16x32_bf16 v[18:21], v[182:185], v[206:209], v[18:21]
	v_mfma_f32_16x16x32_bf16 v[6:9], v[174:177], v[214:217], v[6:9]
	v_mfma_f32_16x16x32_bf16 v[2:5], v[182:185], v[214:217], v[2:5]
	s_setprio 0
	s_barrier
	s_add_i32 s54, 0, 0x18000
	v_add_u32_e32 v153, s54, v148
	s_add_i32 s55, 0, 0x1c000
	ds_read_b128 v[154:157], v153
	ds_read_b128 v[158:161], v153 offset:1024
	ds_read_b128 v[162:165], v153 offset:2048
	ds_read_b128 v[166:169], v153 offset:3072
	v_add_u32_e32 v153, s55, v148
	ds_read_b128 v[170:173], v153
	ds_read_b128 v[174:177], v153 offset:1024
	ds_read_b128 v[178:181], v153 offset:2048
	ds_read_b128 v[182:185], v153 offset:3072
	s_add_u32 s34, s34, 0x40000
	s_addc_u32 s35, s35, 0
	s_mov_b32 m0, s42
	s_nop 0
	ds_read_b128 v[186:189], v152 offset:32768
	ds_read_b128 v[190:193], v152 offset:33792
	ds_read_b128 v[194:197], v152 offset:34816
	ds_read_b128 v[198:201], v152 offset:35840
	ds_read_b128 v[202:205], v152 offset:36864
	ds_read_b128 v[206:209], v152 offset:37888
	ds_read_b128 v[210:213], v152 offset:38912
	ds_read_b128 v[214:217], v152 offset:39936
	global_load_lds_dwordx4 v136, s[34:35]
	v_lshl_add_u64 v[224:225], s[34:35], 0, v[132:133]
	s_mov_b32 m0, s43
	s_nop 0
	global_load_lds_dwordx4 v[224:225], off
	s_waitcnt vmcnt(8)
	s_waitcnt lgkmcnt(0)
	s_barrier
	s_setprio 1
	s_waitcnt lgkmcnt(0)
	v_mfma_f32_16x16x32_bf16 v[126:129], v[154:157], v[186:189], v[126:129]
	v_mfma_f32_16x16x32_bf16 v[122:125], v[162:165], v[186:189], v[122:125]
	v_mfma_f32_16x16x32_bf16 v[110:113], v[154:157], v[194:197], v[110:113]
	v_mfma_f32_16x16x32_bf16 v[106:109], v[162:165], v[194:197], v[106:109]
	v_mfma_f32_16x16x32_bf16 v[94:97], v[154:157], v[202:205], v[94:97]
	v_mfma_f32_16x16x32_bf16 v[90:93], v[162:165], v[202:205], v[90:93]
	v_mfma_f32_16x16x32_bf16 v[78:81], v[154:157], v[210:213], v[78:81]
	v_mfma_f32_16x16x32_bf16 v[74:77], v[162:165], v[210:213], v[74:77]
	v_mfma_f32_16x16x32_bf16 v[126:129], v[158:161], v[190:193], v[126:129]
	v_mfma_f32_16x16x32_bf16 v[122:125], v[166:169], v[190:193], v[122:125]
	v_mfma_f32_16x16x32_bf16 v[110:113], v[158:161], v[198:201], v[110:113]
	v_mfma_f32_16x16x32_bf16 v[106:109], v[166:169], v[198:201], v[106:109]
	v_mfma_f32_16x16x32_bf16 v[94:97], v[158:161], v[206:209], v[94:97]
	v_mfma_f32_16x16x32_bf16 v[90:93], v[166:169], v[206:209], v[90:93]
	v_mfma_f32_16x16x32_bf16 v[78:81], v[158:161], v[214:217], v[78:81]
	v_mfma_f32_16x16x32_bf16 v[74:77], v[166:169], v[214:217], v[74:77]
	s_setprio 0
	s_setprio 1
	v_mfma_f32_16x16x32_bf16 v[118:121], v[170:173], v[186:189], v[118:121]
	v_mfma_f32_16x16x32_bf16 v[114:117], v[178:181], v[186:189], v[114:117]
	v_mfma_f32_16x16x32_bf16 v[102:105], v[170:173], v[194:197], v[102:105]
	v_mfma_f32_16x16x32_bf16 v[98:101], v[178:181], v[194:197], v[98:101]
	v_mfma_f32_16x16x32_bf16 v[86:89], v[170:173], v[202:205], v[86:89]
	v_mfma_f32_16x16x32_bf16 v[82:85], v[178:181], v[202:205], v[82:85]
	v_mfma_f32_16x16x32_bf16 v[70:73], v[170:173], v[210:213], v[70:73]
	v_mfma_f32_16x16x32_bf16 v[66:69], v[178:181], v[210:213], v[66:69]
	v_mfma_f32_16x16x32_bf16 v[118:121], v[174:177], v[190:193], v[118:121]
	v_mfma_f32_16x16x32_bf16 v[114:117], v[182:185], v[190:193], v[114:117]
	v_mfma_f32_16x16x32_bf16 v[102:105], v[174:177], v[198:201], v[102:105]
	v_mfma_f32_16x16x32_bf16 v[98:101], v[182:185], v[198:201], v[98:101]
	v_mfma_f32_16x16x32_bf16 v[86:89], v[174:177], v[206:209], v[86:89]
	v_mfma_f32_16x16x32_bf16 v[82:85], v[182:185], v[206:209], v[82:85]
	v_mfma_f32_16x16x32_bf16 v[70:73], v[174:177], v[214:217], v[70:73]
	v_mfma_f32_16x16x32_bf16 v[66:69], v[182:185], v[214:217], v[66:69]
	s_setprio 0
	s_barrier
	s_add_i32 s34, s54, s38
	v_lshl_add_u64 v[146:147], v[146:147], 0, s[12:13]
	s_mov_b32 m0, s34
	ds_read_b128 v[186:189], v152 offset:49152
	ds_read_b128 v[190:193], v152 offset:50176
	ds_read_b128 v[194:197], v152 offset:51200
	ds_read_b128 v[198:201], v152 offset:52224
	ds_read_b128 v[202:205], v152 offset:53248
	ds_read_b128 v[206:209], v152 offset:54272
	ds_read_b128 v[210:213], v152 offset:55296
	ds_read_b128 v[214:217], v152 offset:56320
	global_load_lds_dwordx4 v[146:147], off
	s_add_i32 m0, s34, 0x2000
	s_add_u32 s30, s30, 0x40080
	v_lshl_add_u64 v[146:147], v[218:219], 0, s[12:13]
	s_addc_u32 s31, s31, 0
	s_add_i32 s34, s55, s38
	global_load_lds_dwordx4 v[146:147], off
	s_nop 0
	s_mov_b32 m0, s34
	s_nop 0
	global_load_lds_dwordx4 v134, s[30:31]
	s_nop 0
	s_add_i32 m0, s34, 0x2000
	s_nop 0
	global_load_lds_dwordx4 v130, s[30:31]
	v_lshl_add_u64 v[146:147], v[220:221], 0, s[12:13]
	s_mov_b32 m0, s45
	s_nop 0
	global_load_lds_dwordx4 v[146:147], off
	v_lshl_add_u64 v[146:147], v[222:223], 0, s[12:13]
	s_mov_b32 m0, s46
	s_nop 0
	global_load_lds_dwordx4 v[146:147], off
	s_waitcnt vmcnt(8)
	s_waitcnt lgkmcnt(0)
	s_barrier
	s_setprio 1
	s_waitcnt lgkmcnt(0)
	v_mfma_f32_16x16x32_bf16 v[62:65], v[154:157], v[186:189], v[62:65]
	v_mfma_f32_16x16x32_bf16 v[58:61], v[162:165], v[186:189], v[58:61]
	v_mfma_f32_16x16x32_bf16 v[46:49], v[154:157], v[194:197], v[46:49]
	v_mfma_f32_16x16x32_bf16 v[42:45], v[162:165], v[194:197], v[42:45]
	v_mfma_f32_16x16x32_bf16 v[30:33], v[154:157], v[202:205], v[30:33]
	v_mfma_f32_16x16x32_bf16 v[26:29], v[162:165], v[202:205], v[26:29]
	v_mfma_f32_16x16x32_bf16 v[14:17], v[154:157], v[210:213], v[14:17]
	v_mfma_f32_16x16x32_bf16 v[10:13], v[162:165], v[210:213], v[10:13]
	v_mfma_f32_16x16x32_bf16 v[62:65], v[158:161], v[190:193], v[62:65]
	v_mfma_f32_16x16x32_bf16 v[58:61], v[166:169], v[190:193], v[58:61]
	v_mfma_f32_16x16x32_bf16 v[46:49], v[158:161], v[198:201], v[46:49]
	v_mfma_f32_16x16x32_bf16 v[42:45], v[166:169], v[198:201], v[42:45]
	v_mfma_f32_16x16x32_bf16 v[30:33], v[158:161], v[206:209], v[30:33]
	v_mfma_f32_16x16x32_bf16 v[26:29], v[166:169], v[206:209], v[26:29]
	v_mfma_f32_16x16x32_bf16 v[14:17], v[158:161], v[214:217], v[14:17]
	v_mfma_f32_16x16x32_bf16 v[10:13], v[166:169], v[214:217], v[10:13]
	s_setprio 0
	s_setprio 1
	v_mfma_f32_16x16x32_bf16 v[54:57], v[170:173], v[186:189], v[54:57]
	v_mfma_f32_16x16x32_bf16 v[50:53], v[178:181], v[186:189], v[50:53]
	v_mfma_f32_16x16x32_bf16 v[38:41], v[170:173], v[194:197], v[38:41]
	v_mfma_f32_16x16x32_bf16 v[34:37], v[178:181], v[194:197], v[34:37]
	v_mfma_f32_16x16x32_bf16 v[22:25], v[170:173], v[202:205], v[22:25]
	v_mfma_f32_16x16x32_bf16 v[18:21], v[178:181], v[202:205], v[18:21]
	v_mfma_f32_16x16x32_bf16 v[6:9], v[170:173], v[210:213], v[6:9]
	v_mfma_f32_16x16x32_bf16 v[2:5], v[178:181], v[210:213], v[2:5]
	v_mfma_f32_16x16x32_bf16 v[54:57], v[174:177], v[190:193], v[54:57]
	v_mfma_f32_16x16x32_bf16 v[50:53], v[182:185], v[190:193], v[50:53]
	v_mfma_f32_16x16x32_bf16 v[38:41], v[174:177], v[198:201], v[38:41]
	v_mfma_f32_16x16x32_bf16 v[34:37], v[182:185], v[198:201], v[34:37]
	v_mfma_f32_16x16x32_bf16 v[22:25], v[174:177], v[206:209], v[22:25]
	v_mfma_f32_16x16x32_bf16 v[18:21], v[182:185], v[206:209], v[18:21]
	v_mfma_f32_16x16x32_bf16 v[6:9], v[174:177], v[214:217], v[6:9]
	v_mfma_f32_16x16x32_bf16 v[2:5], v[182:185], v[214:217], v[2:5]
	s_setprio 0
	s_barrier
	s_add_i32 s53, s53, 2
	s_add_u32 s28, s28, 0x100
	s_addc_u32 s29, s29, 0
	s_add_u32 s21, s21, 0x100
	s_addc_u32 s52, s52, 0
	s_cmp_gt_u32 s53, 13
	s_cbranch_scc0 .LBB0_86
	s_and_b64 vcc, exec, s[14:15]
	s_cbranch_vccz .LBB0_89
	s_barrier

.LBB0_124:
	s_add_u32 s6, s6, 0x6900000
	s_addc_u32 s7, s7, 0
	s_lshl_b32 s3, s3, 5
	s_mov_b64 s[12:13], 0x80
	s_and_b32 s3, s3, 0x60
	s_add_i32 m0, s42, 0x18000
	v_lshl_add_u64 v[8:9], v[8:9], 0, s[12:13]
	s_lshl_b32 s5, s2, 13
	s_lshl_b32 s16, s3, 7
	s_waitcnt vmcnt(2)
	s_barrier
	global_load_lds_dwordx4 v[8:9], off
	v_lshl_add_u64 v[6:7], v[6:7], 0, s[12:13]
	s_add_i32 m0, s42, 0x1a000
	s_add_i32 s47, s42, 0x8000
	s_add_i32 s48, s42, 0xa000
	global_load_lds_dwordx4 v[6:7], off
	v_lshl_add_u64 v[2:3], v[2:3], 0, s[12:13]
	s_mov_b32 m0, s47
	s_add_u32 s14, s30, 0xb0080
	global_load_lds_dwordx4 v[2:3], off
	v_lshl_add_u64 v[2:3], v[4:5], 0, s[12:13]
	s_mov_b32 m0, s48
	s_addc_u32 s15, s31, 0
	global_load_lds_dwordx4 v[2:3], off
	s_add_i32 m0, s42, 0x1c000
	s_nop 0
	global_load_lds_dwordx4 v132, s[14:15]
	s_nop 0
	s_add_i32 m0, s42, 0x1e000
	v_lshlrev_b32_e32 v4, 2, v10
	global_load_lds_dwordx4 v136, s[14:15]
	v_and_b32_e32 v2, 15, v10
	v_lshl_or_b32 v1, s2, 6, v2
	v_lshlrev_b32_e32 v3, 1, v13
	v_lshlrev_b32_e32 v5, 6, v10
	s_movk_i32 s2, 0x3c0
	v_lshl_or_b32 v2, v2, 6, v3
	v_and_b32_e32 v4, 32, v4
	v_and_or_b32 v3, v5, s2, v3
	v_bitop3_b32 v146, s16, v3, v4 bitop3:0xf6
	s_waitcnt vmcnt(6)
	s_cmpk_lt_u32 s10, 0x100
	v_add_u16_e32 v3, v11, v12
	v_bitop3_b32 v2, v2, s5, v4 bitop3:0xde
	s_cselect_b64 s[14:15], -1, 0
	v_lshrrev_b16_e32 v3, 1, v3
	s_add_i32 s50, 0, 0x10000
	s_add_i32 s51, 0, 0x14000
	s_sext_i32_i8 s59, s4
	s_ashr_i32 s49, s11, 31
	v_or_b32_e32 v147, s3, v13
	v_add_lshl_u32 v138, v14, v3, 1
	v_mov_b32_e32 v139, v133
	v_add_lshl_u32 v140, v15, v3, 1
	v_mov_b32_e32 v141, v133
	v_mov_b64_e32 v[142:143], 0x200
	v_mov_b64_e32 v[144:145], 0x1ff
	v_add_u32_e32 v148, s50, v146
	v_add_u32_e32 v149, s51, v146
	v_add_u32_e32 v150, 0, v2
	s_mov_b64 s[16:17], 0x40000
	s_mov_b32 s52, 0x40000
	s_mov_b64 s[18:19], 0x48000
	s_mov_b32 s53, 0x48000
	s_mov_b64 s[22:23], 0x50000
	s_mov_b32 s54, 0x50000
	s_mov_b64 s[24:25], 0x58000
	s_mov_b32 s55, 0x58000
	s_barrier
	s_branch .LBB0_127

.LBB0_138:
	ds_read_b128 v[152:155], v148
	ds_read_b128 v[156:159], v148 offset:1024
	ds_read_b128 v[160:163], v148 offset:2048
	ds_read_b128 v[164:167], v148 offset:3072
	ds_read_b128 v[168:171], v149
	ds_read_b128 v[172:175], v149 offset:1024
	ds_read_b128 v[176:179], v149 offset:2048
	ds_read_b128 v[180:183], v149 offset:3072
	s_add_u32 s30, s28, 0xfff50080
	s_addc_u32 s31, s29, -1
	s_cmp_eq_u32 s21, 40
	s_cselect_b32 s35, s5, s31
	s_cselect_b32 s34, s4, s30
	s_cselect_b32 s31, s27, s20
	s_cselect_b32 s30, s26, s10
	s_nop 0
	s_add_i32 m0, s42, 0xc000
	ds_read_b128 v[184:187], v150
	ds_read_b128 v[188:191], v150 offset:1024
	ds_read_b128 v[192:195], v150 offset:2048
	ds_read_b128 v[196:199], v150 offset:3072
	ds_read_b128 v[200:203], v150 offset:4096
	ds_read_b128 v[204:207], v150 offset:5120
	ds_read_b128 v[208:211], v150 offset:6144
	ds_read_b128 v[212:215], v150 offset:7168
	global_load_lds_dwordx4 v138, s[28:29]
	s_nop 0
	s_add_i32 m0, s42, 0xe000
	s_nop 0
	global_load_lds_dwordx4 v140, s[28:29]
	s_waitcnt vmcnt(8)
	s_waitcnt lgkmcnt(0)
	s_barrier
	s_setprio 1
	s_waitcnt lgkmcnt(0)
	v_mfma_f32_16x16x32_bf16 v[126:129], v[152:155], v[184:187], v[126:129]
	v_mfma_f32_16x16x32_bf16 v[122:125], v[160:163], v[184:187], v[122:125]
	v_mfma_f32_16x16x32_bf16 v[118:121], v[152:155], v[192:195], v[118:121]
	v_mfma_f32_16x16x32_bf16 v[114:117], v[160:163], v[192:195], v[114:117]
	v_mfma_f32_16x16x32_bf16 v[102:105], v[152:155], v[200:203], v[102:105]
	v_mfma_f32_16x16x32_bf16 v[98:101], v[160:163], v[200:203], v[98:101]
	v_mfma_f32_16x16x32_bf16 v[86:89], v[152:155], v[208:211], v[86:89]
	v_mfma_f32_16x16x32_bf16 v[82:85], v[160:163], v[208:211], v[82:85]
	v_mfma_f32_16x16x32_bf16 v[126:129], v[156:159], v[188:191], v[126:129]
	v_mfma_f32_16x16x32_bf16 v[122:125], v[164:167], v[188:191], v[122:125]
	v_mfma_f32_16x16x32_bf16 v[118:121], v[156:159], v[196:199], v[118:121]
	v_mfma_f32_16x16x32_bf16 v[114:117], v[164:167], v[196:199], v[114:117]
	v_mfma_f32_16x16x32_bf16 v[102:105], v[156:159], v[204:207], v[102:105]
	v_mfma_f32_16x16x32_bf16 v[98:101], v[164:167], v[204:207], v[98:101]
	v_mfma_f32_16x16x32_bf16 v[86:89], v[156:159], v[212:215], v[86:89]
	v_mfma_f32_16x16x32_bf16 v[82:85], v[164:167], v[212:215], v[82:85]
	s_setprio 0
	s_setprio 1
	v_mfma_f32_16x16x32_bf16 v[110:113], v[168:171], v[184:187], v[110:113]
	v_mfma_f32_16x16x32_bf16 v[106:109], v[176:179], v[184:187], v[106:109]
	v_mfma_f32_16x16x32_bf16 v[94:97], v[168:171], v[192:195], v[94:97]
	v_mfma_f32_16x16x32_bf16 v[90:93], v[176:179], v[192:195], v[90:93]
	v_mfma_f32_16x16x32_bf16 v[78:81], v[168:171], v[200:203], v[78:81]
	v_mfma_f32_16x16x32_bf16 v[74:77], v[176:179], v[200:203], v[74:77]
	v_mfma_f32_16x16x32_bf16 v[70:73], v[168:171], v[208:211], v[70:73]
	v_mfma_f32_16x16x32_bf16 v[66:69], v[176:179], v[208:211], v[66:69]
	v_mfma_f32_16x16x32_bf16 v[110:113], v[172:175], v[188:191], v[110:113]
	v_mfma_f32_16x16x32_bf16 v[106:109], v[180:183], v[188:191], v[106:109]
	v_mfma_f32_16x16x32_bf16 v[94:97], v[172:175], v[196:199], v[94:97]
	v_mfma_f32_16x16x32_bf16 v[90:93], v[180:183], v[196:199], v[90:93]
	v_mfma_f32_16x16x32_bf16 v[78:81], v[172:175], v[204:207], v[78:81]
	v_mfma_f32_16x16x32_bf16 v[74:77], v[180:183], v[204:207], v[74:77]
	v_mfma_f32_16x16x32_bf16 v[70:73], v[172:175], v[212:215], v[70:73]
	v_mfma_f32_16x16x32_bf16 v[66:69], v[180:183], v[212:215], v[66:69]
	s_setprio 0
	s_barrier
	s_add_i32 s60, s50, s41
	v_lshl_add_u64 v[216:217], s[30:31], 0, v[132:133]
	s_mov_b32 m0, s60
	ds_read_b128 v[184:187], v150 offset:16384
	ds_read_b128 v[188:191], v150 offset:17408
	ds_read_b128 v[192:195], v150 offset:18432
	ds_read_b128 v[196:199], v150 offset:19456
	ds_read_b128 v[200:203], v150 offset:20480
	ds_read_b128 v[204:207], v150 offset:21504
	ds_read_b128 v[208:211], v150 offset:22528
	ds_read_b128 v[212:215], v150 offset:23552
	global_load_lds_dwordx4 v[216:217], off
	s_add_i32 m0, s60, 0x2000
	s_add_u32 s60, s30, 0xb0000
	v_lshl_add_u64 v[218:219], s[30:31], 0, v[136:137]
	s_addc_u32 s61, s31, 0
	s_add_i32 s62, s51, s41
	global_load_lds_dwordx4 v[218:219], off
	s_nop 0
	s_mov_b32 m0, s62
	v_lshl_add_u64 v[222:223], s[34:35], 0, v[134:135]
	global_load_lds_dwordx4 v132, s[60:61]
	s_nop 0
	s_add_i32 m0, s62, 0x2000
	s_nop 0
	global_load_lds_dwordx4 v136, s[60:61]
	v_lshl_add_u64 v[220:221], s[34:35], 0, v[130:131]
	s_mov_b32 m0, s42
	s_nop 0
	global_load_lds_dwordx4 v[220:221], off
	s_mov_b32 m0, s43
	s_nop 0
	global_load_lds_dwordx4 v[222:223], off
	s_waitcnt vmcnt(8)
	s_waitcnt lgkmcnt(0)
	s_barrier
	s_setprio 1
	s_waitcnt lgkmcnt(0)
	v_mfma_f32_16x16x32_bf16 v[62:65], v[152:155], v[184:187], v[62:65]
	v_mfma_f32_16x16x32_bf16 v[58:61], v[160:163], v[184:187], v[58:61]
	v_mfma_f32_16x16x32_bf16 v[54:57], v[152:155], v[192:195], v[54:57]
	v_mfma_f32_16x16x32_bf16 v[50:53], v[160:163], v[192:195], v[50:53]
	v_mfma_f32_16x16x32_bf16 v[38:41], v[152:155], v[200:203], v[38:41]
	v_mfma_f32_16x16x32_bf16 v[34:37], v[160:163], v[200:203], v[34:37]
	v_mfma_f32_16x16x32_bf16 v[22:25], v[152:155], v[208:211], v[22:25]
	v_mfma_f32_16x16x32_bf16 v[18:21], v[160:163], v[208:211], v[18:21]
	v_mfma_f32_16x16x32_bf16 v[62:65], v[156:159], v[188:191], v[62:65]
	v_mfma_f32_16x16x32_bf16 v[58:61], v[164:167], v[188:191], v[58:61]
	v_mfma_f32_16x16x32_bf16 v[54:57], v[156:159], v[196:199], v[54:57]
	v_mfma_f32_16x16x32_bf16 v[50:53], v[164:167], v[196:199], v[50:53]
	v_mfma_f32_16x16x32_bf16 v[38:41], v[156:159], v[204:207], v[38:41]
	v_mfma_f32_16x16x32_bf16 v[34:37], v[164:167], v[204:207], v[34:37]
	v_mfma_f32_16x16x32_bf16 v[22:25], v[156:159], v[212:215], v[22:25]
	v_mfma_f32_16x16x32_bf16 v[18:21], v[164:167], v[212:215], v[18:21]
	s_setprio 0
	s_setprio 1
	v_mfma_f32_16x16x32_bf16 v[46:49], v[168:171], v[184:187], v[46:49]
	v_mfma_f32_16x16x32_bf16 v[42:45], v[176:179], v[184:187], v[42:45]
	v_mfma_f32_16x16x32_bf16 v[30:33], v[168:171], v[192:195], v[30:33]
	v_mfma_f32_16x16x32_bf16 v[26:29], v[176:179], v[192:195], v[26:29]
	v_mfma_f32_16x16x32_bf16 v[14:17], v[168:171], v[200:203], v[14:17]
	v_mfma_f32_16x16x32_bf16 v[10:13], v[176:179], v[200:203], v[10:13]
	v_mfma_f32_16x16x32_bf16 v[6:9], v[168:171], v[208:211], v[6:9]
	v_mfma_f32_16x16x32_bf16 v[2:5], v[176:179], v[208:211], v[2:5]
	v_mfma_f32_16x16x32_bf16 v[46:49], v[172:175], v[188:191], v[46:49]
	v_mfma_f32_16x16x32_bf16 v[42:45], v[180:183], v[188:191], v[42:45]
	v_mfma_f32_16x16x32_bf16 v[30:33], v[172:175], v[196:199], v[30:33]
	v_mfma_f32_16x16x32_bf16 v[26:29], v[180:183], v[196:199], v[26:29]
	v_mfma_f32_16x16x32_bf16 v[14:17], v[172:175], v[204:207], v[14:17]
	v_mfma_f32_16x16x32_bf16 v[10:13], v[180:183], v[204:207], v[10:13]
	v_mfma_f32_16x16x32_bf16 v[6:9], v[172:175], v[212:215], v[6:9]
	v_mfma_f32_16x16x32_bf16 v[2:5], v[180:183], v[212:215], v[2:5]
	s_setprio 0
	s_barrier
	s_add_i32 s60, 0, 0x18000
	v_add_u32_e32 v151, s60, v146
	s_add_i32 s61, 0, 0x1c000
	ds_read_b128 v[152:155], v151
	ds_read_b128 v[156:159], v151 offset:1024
	ds_read_b128 v[160:163], v151 offset:2048
	ds_read_b128 v[164:167], v151 offset:3072
	v_add_u32_e32 v151, s61, v146
	ds_read_b128 v[168:171], v151
	ds_read_b128 v[172:175], v151 offset:1024
	ds_read_b128 v[176:179], v151 offset:2048
	ds_read_b128 v[180:183], v151 offset:3072
	s_add_u32 s34, s34, 0xb0000
	s_addc_u32 s35, s35, 0
	s_mov_b32 m0, s44
	s_nop 0
	ds_read_b128 v[184:187], v150 offset:32768
	ds_read_b128 v[188:191], v150 offset:33792
	ds_read_b128 v[192:195], v150 offset:34816
	ds_read_b128 v[196:199], v150 offset:35840
	ds_read_b128 v[200:203], v150 offset:36864
	ds_read_b128 v[204:207], v150 offset:37888
	ds_read_b128 v[208:211], v150 offset:38912
	ds_read_b128 v[212:215], v150 offset:39936
	global_load_lds_dwordx4 v130, s[34:35]
	v_lshl_add_u64 v[224:225], s[34:35], 0, v[134:135]
	s_mov_b32 m0, s45
	s_nop 0
	global_load_lds_dwordx4 v[224:225], off
	s_waitcnt vmcnt(8)
	s_waitcnt lgkmcnt(0)
	s_barrier
	s_setprio 1
	s_waitcnt lgkmcnt(0)
	v_mfma_f32_16x16x32_bf16 v[126:129], v[152:155], v[184:187], v[126:129]
	v_mfma_f32_16x16x32_bf16 v[122:125], v[160:163], v[184:187], v[122:125]
	v_mfma_f32_16x16x32_bf16 v[118:121], v[152:155], v[192:195], v[118:121]
	v_mfma_f32_16x16x32_bf16 v[114:117], v[160:163], v[192:195], v[114:117]
	v_mfma_f32_16x16x32_bf16 v[102:105], v[152:155], v[200:203], v[102:105]
	v_mfma_f32_16x16x32_bf16 v[98:101], v[160:163], v[200:203], v[98:101]
	v_mfma_f32_16x16x32_bf16 v[86:89], v[152:155], v[208:211], v[86:89]
	v_mfma_f32_16x16x32_bf16 v[82:85], v[160:163], v[208:211], v[82:85]
	v_mfma_f32_16x16x32_bf16 v[126:129], v[156:159], v[188:191], v[126:129]
	v_mfma_f32_16x16x32_bf16 v[122:125], v[164:167], v[188:191], v[122:125]
	v_mfma_f32_16x16x32_bf16 v[118:121], v[156:159], v[196:199], v[118:121]
	v_mfma_f32_16x16x32_bf16 v[114:117], v[164:167], v[196:199], v[114:117]
	v_mfma_f32_16x16x32_bf16 v[102:105], v[156:159], v[204:207], v[102:105]
	v_mfma_f32_16x16x32_bf16 v[98:101], v[164:167], v[204:207], v[98:101]
	v_mfma_f32_16x16x32_bf16 v[86:89], v[156:159], v[212:215], v[86:89]
	v_mfma_f32_16x16x32_bf16 v[82:85], v[164:167], v[212:215], v[82:85]
	s_setprio 0
	s_setprio 1
	v_mfma_f32_16x16x32_bf16 v[110:113], v[168:171], v[184:187], v[110:113]
	v_mfma_f32_16x16x32_bf16 v[106:109], v[176:179], v[184:187], v[106:109]
	v_mfma_f32_16x16x32_bf16 v[94:97], v[168:171], v[192:195], v[94:97]
	v_mfma_f32_16x16x32_bf16 v[90:93], v[176:179], v[192:195], v[90:93]
	v_mfma_f32_16x16x32_bf16 v[78:81], v[168:171], v[200:203], v[78:81]
	v_mfma_f32_16x16x32_bf16 v[74:77], v[176:179], v[200:203], v[74:77]
	v_mfma_f32_16x16x32_bf16 v[70:73], v[168:171], v[208:211], v[70:73]
	v_mfma_f32_16x16x32_bf16 v[66:69], v[176:179], v[208:211], v[66:69]
	v_mfma_f32_16x16x32_bf16 v[110:113], v[172:175], v[188:191], v[110:113]
	v_mfma_f32_16x16x32_bf16 v[106:109], v[180:183], v[188:191], v[106:109]
	v_mfma_f32_16x16x32_bf16 v[94:97], v[172:175], v[196:199], v[94:97]
	v_mfma_f32_16x16x32_bf16 v[90:93], v[180:183], v[196:199], v[90:93]
	v_mfma_f32_16x16x32_bf16 v[78:81], v[172:175], v[204:207], v[78:81]
	v_mfma_f32_16x16x32_bf16 v[74:77], v[180:183], v[204:207], v[74:77]
	v_mfma_f32_16x16x32_bf16 v[70:73], v[172:175], v[212:215], v[70:73]
	v_mfma_f32_16x16x32_bf16 v[66:69], v[180:183], v[212:215], v[66:69]
	s_setprio 0
	s_barrier
	s_add_i32 s34, s60, s41
	v_lshl_add_u64 v[216:217], v[216:217], 0, s[12:13]
	s_mov_b32 m0, s34
	ds_read_b128 v[184:187], v150 offset:49152
	ds_read_b128 v[188:191], v150 offset:50176
	ds_read_b128 v[192:195], v150 offset:51200
	ds_read_b128 v[196:199], v150 offset:52224
	ds_read_b128 v[200:203], v150 offset:53248
	ds_read_b128 v[204:207], v150 offset:54272
	ds_read_b128 v[208:211], v150 offset:55296
	ds_read_b128 v[212:215], v150 offset:56320
	global_load_lds_dwordx4 v[216:217], off
	s_add_i32 m0, s34, 0x2000
	s_add_u32 s30, s30, 0xb0080
	v_lshl_add_u64 v[216:217], v[218:219], 0, s[12:13]
	s_addc_u32 s31, s31, 0
	s_add_i32 s34, s61, s41
	global_load_lds_dwordx4 v[216:217], off
	s_nop 0
	s_mov_b32 m0, s34
	s_nop 0
	global_load_lds_dwordx4 v132, s[30:31]
	s_nop 0
	s_add_i32 m0, s34, 0x2000
	s_nop 0
	global_load_lds_dwordx4 v136, s[30:31]
	v_lshl_add_u64 v[216:217], v[220:221], 0, s[12:13]
	s_mov_b32 m0, s47
	s_nop 0
	global_load_lds_dwordx4 v[216:217], off
	v_lshl_add_u64 v[216:217], v[222:223], 0, s[12:13]
	s_mov_b32 m0, s48
	s_nop 0
	global_load_lds_dwordx4 v[216:217], off
	s_waitcnt vmcnt(8)
	s_waitcnt lgkmcnt(0)
	s_barrier
	s_setprio 1
	s_waitcnt lgkmcnt(0)
	v_mfma_f32_16x16x32_bf16 v[62:65], v[152:155], v[184:187], v[62:65]
	v_mfma_f32_16x16x32_bf16 v[58:61], v[160:163], v[184:187], v[58:61]
	v_mfma_f32_16x16x32_bf16 v[54:57], v[152:155], v[192:195], v[54:57]
	v_mfma_f32_16x16x32_bf16 v[50:53], v[160:163], v[192:195], v[50:53]
	v_mfma_f32_16x16x32_bf16 v[38:41], v[152:155], v[200:203], v[38:41]
	v_mfma_f32_16x16x32_bf16 v[34:37], v[160:163], v[200:203], v[34:37]
	v_mfma_f32_16x16x32_bf16 v[22:25], v[152:155], v[208:211], v[22:25]
	v_mfma_f32_16x16x32_bf16 v[18:21], v[160:163], v[208:211], v[18:21]
	v_mfma_f32_16x16x32_bf16 v[62:65], v[156:159], v[188:191], v[62:65]
	v_mfma_f32_16x16x32_bf16 v[58:61], v[164:167], v[188:191], v[58:61]
	v_mfma_f32_16x16x32_bf16 v[54:57], v[156:159], v[196:199], v[54:57]
	v_mfma_f32_16x16x32_bf16 v[50:53], v[164:167], v[196:199], v[50:53]
	v_mfma_f32_16x16x32_bf16 v[38:41], v[156:159], v[204:207], v[38:41]
	v_mfma_f32_16x16x32_bf16 v[34:37], v[164:167], v[204:207], v[34:37]
	v_mfma_f32_16x16x32_bf16 v[22:25], v[156:159], v[212:215], v[22:25]
	v_mfma_f32_16x16x32_bf16 v[18:21], v[164:167], v[212:215], v[18:21]
	s_setprio 0
	s_setprio 1
	v_mfma_f32_16x16x32_bf16 v[46:49], v[168:171], v[184:187], v[46:49]
	v_mfma_f32_16x16x32_bf16 v[42:45], v[176:179], v[184:187], v[42:45]
	v_mfma_f32_16x16x32_bf16 v[30:33], v[168:171], v[192:195], v[30:33]
	v_mfma_f32_16x16x32_bf16 v[26:29], v[176:179], v[192:195], v[26:29]
	v_mfma_f32_16x16x32_bf16 v[14:17], v[168:171], v[200:203], v[14:17]
	v_mfma_f32_16x16x32_bf16 v[10:13], v[176:179], v[200:203], v[10:13]
	v_mfma_f32_16x16x32_bf16 v[6:9], v[168:171], v[208:211], v[6:9]
	v_mfma_f32_16x16x32_bf16 v[2:5], v[176:179], v[208:211], v[2:5]
	v_mfma_f32_16x16x32_bf16 v[46:49], v[172:175], v[188:191], v[46:49]
	v_mfma_f32_16x16x32_bf16 v[42:45], v[180:183], v[188:191], v[42:45]
	v_mfma_f32_16x16x32_bf16 v[30:33], v[172:175], v[196:199], v[30:33]
	v_mfma_f32_16x16x32_bf16 v[26:29], v[180:183], v[196:199], v[26:29]
	v_mfma_f32_16x16x32_bf16 v[14:17], v[172:175], v[204:207], v[14:17]
	v_mfma_f32_16x16x32_bf16 v[10:13], v[180:183], v[204:207], v[10:13]
	v_mfma_f32_16x16x32_bf16 v[6:9], v[172:175], v[212:215], v[6:9]
	v_mfma_f32_16x16x32_bf16 v[2:5], v[180:183], v[212:215], v[2:5]
	s_setprio 0
	s_barrier
	s_add_i32 s21, s21, 2
	s_add_u32 s28, s28, 0x100
	s_addc_u32 s29, s29, 0
	s_add_u32 s10, s10, 0x100
	s_addc_u32 s20, s20, 0
	s_cmp_gt_u32 s21, 41
	s_cbranch_scc0 .LBB0_138
	s_and_b64 vcc, exec, s[14:15]
	s_cbranch_vccz .LBB0_141
	s_barrier

.LBB0_203:
	s_add_u32 s16, s14, 0xa900000
	s_addc_u32 s17, s15, 0
	s_add_u32 s14, s14, 0x100000
	s_mov_b64 s[18:19], 0x80
	s_addc_u32 s15, s15, 0
	s_and_b32 s3, s3, 3
	s_add_i32 m0, s45, 0x18000
	v_lshl_add_u64 v[8:9], v[8:9], 0, s[18:19]
	s_lshl_b32 s7, s2, 13
	s_lshl_b32 s20, s3, 5
	s_lshl_b32 s3, s3, 12
	s_waitcnt vmcnt(2)
	s_barrier
	global_load_lds_dwordx4 v[8:9], off
	v_lshl_add_u64 v[6:7], v[6:7], 0, s[18:19]
	s_add_i32 m0, s45, 0x1a000
	s_add_i32 s61, s45, 0x8000
	s_add_i32 s62, s45, 0xa000
	global_load_lds_dwordx4 v[6:7], off
	v_lshl_add_u64 v[2:3], v[2:3], 0, s[18:19]
	s_mov_b32 m0, s61
	s_add_u32 s4, s48, 0x40080
	global_load_lds_dwordx4 v[2:3], off
	v_lshl_add_u64 v[2:3], v[4:5], 0, s[18:19]
	s_mov_b32 m0, s62
	s_addc_u32 s5, s49, 0
	global_load_lds_dwordx4 v[2:3], off
	s_add_i32 m0, s45, 0x1c000
	s_nop 0
	global_load_lds_dwordx4 v156, s[4:5]
	s_nop 0
	s_add_i32 m0, s45, 0x1e000
	v_lshlrev_b32_e32 v5, 2, v10
	global_load_lds_dwordx4 v160, s[4:5]
	v_and_b32_e32 v2, 15, v10
	v_bfe_u32 v3, v10, 4, 2
	v_lshl_or_b32 v1, s2, 6, v2
	v_lshlrev_b32_e32 v4, 4, v3
	v_lshlrev_b32_e32 v6, 6, v10
	s_movk_i32 s2, 0x3c0
	v_lshl_or_b32 v2, v2, 6, v4
	v_and_b32_e32 v5, 32, v5
	v_and_or_b32 v4, v6, s2, v4
	v_bitop3_b32 v194, s3, v4, v5 bitop3:0xf6
	v_lshl_or_b32 v195, v3, 3, s20
	v_cmp_eq_u32_e32 vcc, 0, v3
	v_cmp_gt_u32_e64 s[2:3], 2, v3
	v_lshlrev_b32_e32 v3, 8, v10
	v_and_b32_e32 v3, 0x38000, v3
	v_lshlrev_b32_e32 v4, 11, v13
	v_or3_b32 v3, v11, v3, v4
	s_cmpk_lt_u32 s10, 0x100
	v_add_u32_e32 v168, v3, v12
	v_lshlrev_b32_e32 v3, 4, v14
	v_bitop3_b32 v2, v2, s7, v5 bitop3:0xde
	s_waitcnt vmcnt(6)
	s_cselect_b64 s[22:23], -1, 0
	s_bitcmp0_b32 s10, 6
	v_and_b32_e32 v3, 0x78000, v3
	s_cselect_b64 s[24:25], -1, 0
	v_cndmask_b32_e64 v164, 1.0, -1.0, vcc
	v_or3_b32 v3, v11, v3, v4
	s_add_i32 s66, 0, 0x10000
	s_add_i32 s67, 0, 0x14000
	v_add_u32_e32 v199, 0, v2
	v_mbcnt_lo_u32_b32 v2, -1, 0
	v_or_b32_e32 v196, 0xffffeb00, v195
	v_mov_b32_e32 v165, v164
	v_mov_b32_e32 v166, v164
	v_mov_b32_e32 v167, v164
	s_ashr_i32 s63, s11, 31
	s_ashr_i32 s64, s33, 31
	v_mov_b32_e32 v169, v163
	v_add_u32_e32 v170, v3, v12
	v_mov_b32_e32 v171, v163
	v_mov_b64_e32 v[172:173], 0xe80
	v_mov_b64_e32 v[174:175], 0xe7f
	s_movk_i32 s65, 0x1d1
	v_add_u32_e32 v197, s66, v194
	v_add_u32_e32 v198, s67, v194
	s_movk_i32 s68, 0x2a00
	s_mov_b64 s[26:27], 0x80000
	s_mov_b32 s69, 0x80000
	s_mov_b64 s[28:29], 0x90000
	s_mov_b32 s70, 0x90000
	s_mov_b64 s[30:31], 0xa0000
	s_mov_b32 s71, 0xa0000
	s_mov_b64 s[34:35], 0xb0000
	s_mov_b32 s72, 0xb0000
	v_mbcnt_hi_u32_b32 v200, -1, v2
	v_mov_b32_e32 v201, 0x3e38aa3b
	s_barrier
	s_branch .LBB0_206

.LBB0_209:
	ds_read_b128 v[130:133], v197
	ds_read_b128 v[134:137], v197 offset:1024
	s_waitcnt vmcnt(0)
	ds_read_b128 v[138:141], v197 offset:2048
	ds_read_b128 v[142:145], v197 offset:3072
	ds_read_b128 v[146:149], v198
	ds_read_b128 v[150:153], v198 offset:1024
	ds_read_b128 v[176:179], v198 offset:2048
	ds_read_b128 v[180:183], v198 offset:3072
	s_add_u32 s48, s46, 0xfffc0080
	s_addc_u32 s49, s47, -1
	s_cmp_eq_u32 s73, 12
	s_cselect_b32 s51, s7, s49
	s_cselect_b32 s50, s10, s48
	s_cselect_b32 s49, s20, s39
	s_cselect_b32 s48, s21, s37
	s_waitcnt lgkmcnt(0)
	s_nop 0
	s_add_i32 m0, s45, 0xc000
	ds_read_b128 v[184:187], v199
	ds_read_b128 v[188:191], v199 offset:1024
	ds_read_b128 v[202:205], v199 offset:2048
	ds_read_b128 v[206:209], v199 offset:3072
	ds_read_b128 v[210:213], v199 offset:4096
	ds_read_b128 v[214:217], v199 offset:5120
	ds_read_b128 v[218:221], v199 offset:6144
	ds_read_b128 v[222:225], v199 offset:7168
	global_load_lds_dwordx4 v168, s[46:47]
	s_nop 0
	s_add_i32 m0, s45, 0xe000
	s_nop 0
	global_load_lds_dwordx4 v170, s[46:47]
	s_waitcnt vmcnt(8)
	s_waitcnt lgkmcnt(0)
	s_barrier
	s_setprio 1
	s_waitcnt lgkmcnt(0)
	v_mfma_f32_16x16x32_bf16 v[126:129], v[130:133], v[184:187], v[126:129]
	v_mfma_f32_16x16x32_bf16 v[122:125], v[138:141], v[184:187], v[122:125]
	v_mfma_f32_16x16x32_bf16 v[110:113], v[130:133], v[202:205], v[110:113]
	v_mfma_f32_16x16x32_bf16 v[106:109], v[138:141], v[202:205], v[106:109]
	v_mfma_f32_16x16x32_bf16 v[94:97], v[130:133], v[210:213], v[94:97]
	v_mfma_f32_16x16x32_bf16 v[90:93], v[138:141], v[210:213], v[90:93]
	v_mfma_f32_16x16x32_bf16 v[78:81], v[130:133], v[218:221], v[78:81]
	v_mfma_f32_16x16x32_bf16 v[74:77], v[138:141], v[218:221], v[74:77]
	v_mfma_f32_16x16x32_bf16 v[126:129], v[134:137], v[188:191], v[126:129]
	v_mfma_f32_16x16x32_bf16 v[122:125], v[142:145], v[188:191], v[122:125]
	v_mfma_f32_16x16x32_bf16 v[110:113], v[134:137], v[206:209], v[110:113]
	v_mfma_f32_16x16x32_bf16 v[106:109], v[142:145], v[206:209], v[106:109]
	v_mfma_f32_16x16x32_bf16 v[94:97], v[134:137], v[214:217], v[94:97]
	v_mfma_f32_16x16x32_bf16 v[90:93], v[142:145], v[214:217], v[90:93]
	v_mfma_f32_16x16x32_bf16 v[78:81], v[134:137], v[222:225], v[78:81]
	v_mfma_f32_16x16x32_bf16 v[74:77], v[142:145], v[222:225], v[74:77]
	s_setprio 0
	s_setprio 1
	v_mfma_f32_16x16x32_bf16 v[118:121], v[146:149], v[184:187], v[118:121]
	v_mfma_f32_16x16x32_bf16 v[114:117], v[176:179], v[184:187], v[114:117]
	v_mfma_f32_16x16x32_bf16 v[102:105], v[146:149], v[202:205], v[102:105]
	v_mfma_f32_16x16x32_bf16 v[98:101], v[176:179], v[202:205], v[98:101]
	v_mfma_f32_16x16x32_bf16 v[86:89], v[146:149], v[210:213], v[86:89]
	v_mfma_f32_16x16x32_bf16 v[82:85], v[176:179], v[210:213], v[82:85]
	v_mfma_f32_16x16x32_bf16 v[70:73], v[146:149], v[218:221], v[70:73]
	v_mfma_f32_16x16x32_bf16 v[66:69], v[176:179], v[218:221], v[66:69]
	v_mfma_f32_16x16x32_bf16 v[118:121], v[150:153], v[188:191], v[118:121]
	v_mfma_f32_16x16x32_bf16 v[114:117], v[180:183], v[188:191], v[114:117]
	v_mfma_f32_16x16x32_bf16 v[102:105], v[150:153], v[206:209], v[102:105]
	v_mfma_f32_16x16x32_bf16 v[98:101], v[180:183], v[206:209], v[98:101]
	v_mfma_f32_16x16x32_bf16 v[86:89], v[150:153], v[214:217], v[86:89]
	v_mfma_f32_16x16x32_bf16 v[82:85], v[180:183], v[214:217], v[82:85]
	v_mfma_f32_16x16x32_bf16 v[70:73], v[150:153], v[222:225], v[70:73]
	v_mfma_f32_16x16x32_bf16 v[66:69], v[180:183], v[222:225], v[66:69]
	s_setprio 0
	s_barrier
	s_add_i32 s74, s66, s56
	v_lshl_add_u64 v[192:193], s[48:49], 0, v[156:157]
	s_mov_b32 m0, s74
	ds_read_b128 v[184:187], v199 offset:16384
	ds_read_b128 v[188:191], v199 offset:17408
	ds_read_b128 v[202:205], v199 offset:18432
	ds_read_b128 v[206:209], v199 offset:19456
	ds_read_b128 v[210:213], v199 offset:20480
	ds_read_b128 v[214:217], v199 offset:21504
	ds_read_b128 v[218:221], v199 offset:22528
	ds_read_b128 v[222:225], v199 offset:23552
	global_load_lds_dwordx4 v[192:193], off
	s_add_i32 m0, s74, 0x2000
	s_add_u32 s74, s48, 0x40000
	v_lshl_add_u64 v[226:227], s[48:49], 0, v[160:161]
	s_addc_u32 s75, s49, 0
	s_add_i32 s76, s67, s56
	global_load_lds_dwordx4 v[226:227], off
	s_nop 0
	s_mov_b32 m0, s76
	v_lshl_add_u64 v[230:231], s[50:51], 0, v[158:159]
	global_load_lds_dwordx4 v156, s[74:75]
	s_nop 0
	s_add_i32 m0, s76, 0x2000
	s_nop 0
	global_load_lds_dwordx4 v160, s[74:75]
	v_lshl_add_u64 v[228:229], s[50:51], 0, v[154:155]
	s_mov_b32 m0, s45
	s_nop 0
	global_load_lds_dwordx4 v[228:229], off
	s_mov_b32 m0, s57
	s_nop 0
	global_load_lds_dwordx4 v[230:231], off
	s_waitcnt vmcnt(8)
	s_waitcnt lgkmcnt(0)
	s_barrier
	s_setprio 1
	s_waitcnt lgkmcnt(0)
	v_mfma_f32_16x16x32_bf16 v[62:65], v[130:133], v[184:187], v[62:65]
	v_mfma_f32_16x16x32_bf16 v[58:61], v[138:141], v[184:187], v[58:61]
	v_mfma_f32_16x16x32_bf16 v[46:49], v[130:133], v[202:205], v[46:49]
	v_mfma_f32_16x16x32_bf16 v[42:45], v[138:141], v[202:205], v[42:45]
	v_mfma_f32_16x16x32_bf16 v[30:33], v[130:133], v[210:213], v[30:33]
	v_mfma_f32_16x16x32_bf16 v[26:29], v[138:141], v[210:213], v[26:29]
	v_mfma_f32_16x16x32_bf16 v[14:17], v[130:133], v[218:221], v[14:17]
	v_mfma_f32_16x16x32_bf16 v[10:13], v[138:141], v[218:221], v[10:13]
	v_mfma_f32_16x16x32_bf16 v[62:65], v[134:137], v[188:191], v[62:65]
	v_mfma_f32_16x16x32_bf16 v[58:61], v[142:145], v[188:191], v[58:61]
	v_mfma_f32_16x16x32_bf16 v[46:49], v[134:137], v[206:209], v[46:49]
	v_mfma_f32_16x16x32_bf16 v[42:45], v[142:145], v[206:209], v[42:45]
	v_mfma_f32_16x16x32_bf16 v[30:33], v[134:137], v[214:217], v[30:33]
	v_mfma_f32_16x16x32_bf16 v[26:29], v[142:145], v[214:217], v[26:29]
	v_mfma_f32_16x16x32_bf16 v[14:17], v[134:137], v[222:225], v[14:17]
	v_mfma_f32_16x16x32_bf16 v[10:13], v[142:145], v[222:225], v[10:13]
	s_setprio 0
	s_setprio 1
	v_mfma_f32_16x16x32_bf16 v[54:57], v[146:149], v[184:187], v[54:57]
	v_mfma_f32_16x16x32_bf16 v[50:53], v[176:179], v[184:187], v[50:53]
	v_mfma_f32_16x16x32_bf16 v[38:41], v[146:149], v[202:205], v[38:41]
	v_mfma_f32_16x16x32_bf16 v[34:37], v[176:179], v[202:205], v[34:37]
	v_mfma_f32_16x16x32_bf16 v[22:25], v[146:149], v[210:213], v[22:25]
	v_mfma_f32_16x16x32_bf16 v[18:21], v[176:179], v[210:213], v[18:21]
	v_mfma_f32_16x16x32_bf16 v[6:9], v[146:149], v[218:221], v[6:9]
	v_mfma_f32_16x16x32_bf16 v[2:5], v[176:179], v[218:221], v[2:5]
	v_mfma_f32_16x16x32_bf16 v[54:57], v[150:153], v[188:191], v[54:57]
	v_mfma_f32_16x16x32_bf16 v[50:53], v[180:183], v[188:191], v[50:53]
	v_mfma_f32_16x16x32_bf16 v[38:41], v[150:153], v[206:209], v[38:41]
	v_mfma_f32_16x16x32_bf16 v[34:37], v[180:183], v[206:209], v[34:37]
	v_mfma_f32_16x16x32_bf16 v[22:25], v[150:153], v[214:217], v[22:25]
	v_mfma_f32_16x16x32_bf16 v[18:21], v[180:183], v[214:217], v[18:21]
	v_mfma_f32_16x16x32_bf16 v[6:9], v[150:153], v[222:225], v[6:9]
	v_mfma_f32_16x16x32_bf16 v[2:5], v[180:183], v[222:225], v[2:5]
	s_setprio 0
	s_barrier
	s_add_i32 s74, 0, 0x18000
	s_add_i32 s75, 0, 0x1c000
	v_add_u32_e32 v142, s74, v194
	v_add_u32_e32 v162, s75, v194
	ds_read_b128 v[130:133], v142
	ds_read_b128 v[134:137], v142 offset:1024
	ds_read_b128 v[138:141], v142 offset:2048
	ds_read_b128 v[142:145], v142 offset:3072
	ds_read_b128 v[146:149], v162
	ds_read_b128 v[150:153], v162 offset:1024
	ds_read_b128 v[176:179], v162 offset:2048
	ds_read_b128 v[180:183], v162 offset:3072
	s_add_u32 s50, s50, 0x40000
	s_addc_u32 s51, s51, 0
	s_mov_b32 m0, s58
	s_nop 0
	ds_read_b128 v[184:187], v199 offset:32768
	ds_read_b128 v[188:191], v199 offset:33792
	ds_read_b128 v[202:205], v199 offset:34816
	ds_read_b128 v[206:209], v199 offset:35840
	ds_read_b128 v[210:213], v199 offset:36864
	ds_read_b128 v[214:217], v199 offset:37888
	ds_read_b128 v[218:221], v199 offset:38912
	ds_read_b128 v[222:225], v199 offset:39936
	global_load_lds_dwordx4 v154, s[50:51]
	v_lshl_add_u64 v[232:233], s[50:51], 0, v[158:159]
	s_mov_b32 m0, s59
	s_nop 0
	global_load_lds_dwordx4 v[232:233], off
	s_waitcnt vmcnt(8)
	s_waitcnt lgkmcnt(0)
	s_barrier
	s_setprio 1
	s_waitcnt lgkmcnt(0)
	v_mfma_f32_16x16x32_bf16 v[126:129], v[130:133], v[184:187], v[126:129]
	v_mfma_f32_16x16x32_bf16 v[122:125], v[138:141], v[184:187], v[122:125]
	v_mfma_f32_16x16x32_bf16 v[110:113], v[130:133], v[202:205], v[110:113]
	v_mfma_f32_16x16x32_bf16 v[106:109], v[138:141], v[202:205], v[106:109]
	v_mfma_f32_16x16x32_bf16 v[94:97], v[130:133], v[210:213], v[94:97]
	v_mfma_f32_16x16x32_bf16 v[90:93], v[138:141], v[210:213], v[90:93]
	v_mfma_f32_16x16x32_bf16 v[78:81], v[130:133], v[218:221], v[78:81]
	v_mfma_f32_16x16x32_bf16 v[74:77], v[138:141], v[218:221], v[74:77]
	v_mfma_f32_16x16x32_bf16 v[126:129], v[134:137], v[188:191], v[126:129]
	v_mfma_f32_16x16x32_bf16 v[122:125], v[142:145], v[188:191], v[122:125]
	v_mfma_f32_16x16x32_bf16 v[110:113], v[134:137], v[206:209], v[110:113]
	v_mfma_f32_16x16x32_bf16 v[106:109], v[142:145], v[206:209], v[106:109]
	v_mfma_f32_16x16x32_bf16 v[94:97], v[134:137], v[214:217], v[94:97]
	v_mfma_f32_16x16x32_bf16 v[90:93], v[142:145], v[214:217], v[90:93]
	v_mfma_f32_16x16x32_bf16 v[78:81], v[134:137], v[222:225], v[78:81]
	v_mfma_f32_16x16x32_bf16 v[74:77], v[142:145], v[222:225], v[74:77]
	s_setprio 0
	s_setprio 1
	v_mfma_f32_16x16x32_bf16 v[118:121], v[146:149], v[184:187], v[118:121]
	v_mfma_f32_16x16x32_bf16 v[114:117], v[176:179], v[184:187], v[114:117]
	v_mfma_f32_16x16x32_bf16 v[102:105], v[146:149], v[202:205], v[102:105]
	v_mfma_f32_16x16x32_bf16 v[98:101], v[176:179], v[202:205], v[98:101]
	v_mfma_f32_16x16x32_bf16 v[86:89], v[146:149], v[210:213], v[86:89]
	v_mfma_f32_16x16x32_bf16 v[82:85], v[176:179], v[210:213], v[82:85]
	v_mfma_f32_16x16x32_bf16 v[70:73], v[146:149], v[218:221], v[70:73]
	v_mfma_f32_16x16x32_bf16 v[66:69], v[176:179], v[218:221], v[66:69]
	v_mfma_f32_16x16x32_bf16 v[118:121], v[150:153], v[188:191], v[118:121]
	v_mfma_f32_16x16x32_bf16 v[114:117], v[180:183], v[188:191], v[114:117]
	v_mfma_f32_16x16x32_bf16 v[102:105], v[150:153], v[206:209], v[102:105]
	v_mfma_f32_16x16x32_bf16 v[98:101], v[180:183], v[206:209], v[98:101]
	v_mfma_f32_16x16x32_bf16 v[86:89], v[150:153], v[214:217], v[86:89]
	v_mfma_f32_16x16x32_bf16 v[82:85], v[180:183], v[214:217], v[82:85]
	v_mfma_f32_16x16x32_bf16 v[70:73], v[150:153], v[222:225], v[70:73]
	v_mfma_f32_16x16x32_bf16 v[66:69], v[180:183], v[222:225], v[66:69]
	s_setprio 0
	s_barrier
	s_add_i32 s50, s74, s56
	v_lshl_add_u64 v[192:193], v[192:193], 0, s[18:19]
	s_mov_b32 m0, s50
	ds_read_b128 v[184:187], v199 offset:49152
	ds_read_b128 v[188:191], v199 offset:50176
	ds_read_b128 v[202:205], v199 offset:51200
	ds_read_b128 v[206:209], v199 offset:52224
	ds_read_b128 v[210:213], v199 offset:53248
	ds_read_b128 v[214:217], v199 offset:54272
	ds_read_b128 v[218:221], v199 offset:55296
	ds_read_b128 v[222:225], v199 offset:56320
	global_load_lds_dwordx4 v[192:193], off
	s_add_i32 m0, s50, 0x2000
	s_add_u32 s48, s48, 0x40080
	v_lshl_add_u64 v[192:193], v[226:227], 0, s[18:19]
	s_addc_u32 s49, s49, 0
	s_add_i32 s50, s75, s56
	global_load_lds_dwordx4 v[192:193], off
	s_nop 0
	s_mov_b32 m0, s50
	s_nop 0
	global_load_lds_dwordx4 v156, s[48:49]
	s_nop 0
	s_add_i32 m0, s50, 0x2000
	s_nop 0
	global_load_lds_dwordx4 v160, s[48:49]
	v_lshl_add_u64 v[192:193], v[228:229], 0, s[18:19]
	s_mov_b32 m0, s61
	s_nop 0
	global_load_lds_dwordx4 v[192:193], off
	v_lshl_add_u64 v[192:193], v[230:231], 0, s[18:19]
	s_mov_b32 m0, s62
	s_nop 0
	global_load_lds_dwordx4 v[192:193], off
	s_waitcnt vmcnt(8)
	s_waitcnt lgkmcnt(0)
	s_barrier
	s_setprio 1
	s_waitcnt lgkmcnt(0)
	v_mfma_f32_16x16x32_bf16 v[62:65], v[130:133], v[184:187], v[62:65]
	v_mfma_f32_16x16x32_bf16 v[58:61], v[138:141], v[184:187], v[58:61]
	v_mfma_f32_16x16x32_bf16 v[46:49], v[130:133], v[202:205], v[46:49]
	v_mfma_f32_16x16x32_bf16 v[42:45], v[138:141], v[202:205], v[42:45]
	v_mfma_f32_16x16x32_bf16 v[30:33], v[130:133], v[210:213], v[30:33]
	v_mfma_f32_16x16x32_bf16 v[26:29], v[138:141], v[210:213], v[26:29]
	v_mfma_f32_16x16x32_bf16 v[14:17], v[130:133], v[218:221], v[14:17]
	v_mfma_f32_16x16x32_bf16 v[10:13], v[138:141], v[218:221], v[10:13]
	v_mfma_f32_16x16x32_bf16 v[62:65], v[134:137], v[188:191], v[62:65]
	v_mfma_f32_16x16x32_bf16 v[58:61], v[142:145], v[188:191], v[58:61]
	v_mfma_f32_16x16x32_bf16 v[46:49], v[134:137], v[206:209], v[46:49]
	v_mfma_f32_16x16x32_bf16 v[42:45], v[142:145], v[206:209], v[42:45]
	v_mfma_f32_16x16x32_bf16 v[30:33], v[134:137], v[214:217], v[30:33]
	v_mfma_f32_16x16x32_bf16 v[26:29], v[142:145], v[214:217], v[26:29]
	v_mfma_f32_16x16x32_bf16 v[14:17], v[134:137], v[222:225], v[14:17]
	v_mfma_f32_16x16x32_bf16 v[10:13], v[142:145], v[222:225], v[10:13]
	s_setprio 0
	s_setprio 1
	v_mfma_f32_16x16x32_bf16 v[54:57], v[146:149], v[184:187], v[54:57]
	v_mfma_f32_16x16x32_bf16 v[50:53], v[176:179], v[184:187], v[50:53]
	v_mfma_f32_16x16x32_bf16 v[38:41], v[146:149], v[202:205], v[38:41]
	v_mfma_f32_16x16x32_bf16 v[34:37], v[176:179], v[202:205], v[34:37]
	v_mfma_f32_16x16x32_bf16 v[22:25], v[146:149], v[210:213], v[22:25]
	v_mfma_f32_16x16x32_bf16 v[18:21], v[176:179], v[210:213], v[18:21]
	v_mfma_f32_16x16x32_bf16 v[6:9], v[146:149], v[218:221], v[6:9]
	v_mfma_f32_16x16x32_bf16 v[2:5], v[176:179], v[218:221], v[2:5]
	v_mfma_f32_16x16x32_bf16 v[54:57], v[150:153], v[188:191], v[54:57]
	v_mfma_f32_16x16x32_bf16 v[50:53], v[180:183], v[188:191], v[50:53]
	v_mfma_f32_16x16x32_bf16 v[38:41], v[150:153], v[206:209], v[38:41]
	v_mfma_f32_16x16x32_bf16 v[34:37], v[180:183], v[206:209], v[34:37]
	v_mfma_f32_16x16x32_bf16 v[22:25], v[150:153], v[214:217], v[22:25]
	v_mfma_f32_16x16x32_bf16 v[18:21], v[180:183], v[214:217], v[18:21]
	v_mfma_f32_16x16x32_bf16 v[6:9], v[150:153], v[222:225], v[6:9]
	v_mfma_f32_16x16x32_bf16 v[2:5], v[180:183], v[222:225], v[2:5]
	s_setprio 0
	s_barrier
	s_add_i32 s73, s73, 2
	s_add_u32 s46, s46, 0x100
	s_addc_u32 s47, s47, 0
	s_add_u32 s37, s37, 0x100
	s_addc_u32 s39, s39, 0
	s_cmp_gt_u32 s73, 13
	s_cbranch_scc0 .LBB0_209
	s_and_b64 vcc, exec, s[22:23]
	s_cbranch_vccz .LBB0_212
	s_barrier

.LBB0_502:
	ds_read_b128 v[146:149], v164
	ds_read_b128 v[168:171], v164 offset:1024
	ds_read_b128 v[172:175], v164 offset:2048
	ds_read_b128 v[176:179], v164 offset:3072
	ds_read_b128 v[180:183], v165
	ds_read_b128 v[184:187], v165 offset:1024
	ds_read_b128 v[188:191], v165 offset:2048
	ds_read_b128 v[192:195], v165 offset:3072
	s_add_i32 s60, s21, 2
	s_add_u32 s36, s34, 0xffeb0080
	s_addc_u32 s37, s35, -1
	s_cmp_eq_u32 s52, s21
	s_cselect_b32 s37, s5, s37
	s_cselect_b32 s36, s4, s36
	s_cselect_b32 s63, s31, s20
	s_cselect_b32 s62, s30, s10
	s_nop 0
	s_add_i32 m0, s44, 0xc000
	ds_read_b128 v[196:199], v166
	ds_read_b128 v[200:203], v166 offset:1024
	ds_read_b128 v[204:207], v166 offset:2048
	ds_read_b128 v[208:211], v166 offset:3072
	ds_read_b128 v[212:215], v166 offset:4096
	ds_read_b128 v[216:219], v166 offset:5120
	ds_read_b128 v[220:223], v166 offset:6144
	ds_read_b128 v[224:227], v166 offset:7168
	global_load_lds_dwordx4 v138, s[34:35]
	s_nop 0
	s_add_i32 m0, s44, 0xe000
	s_nop 0
	global_load_lds_dwordx4 v140, s[34:35]
	s_waitcnt vmcnt(8)
	s_waitcnt lgkmcnt(0)
	s_barrier
	s_setprio 1
	s_waitcnt lgkmcnt(0)
	v_mfma_f32_16x16x32_bf16 v[126:129], v[146:149], v[196:199], v[126:129]
	v_mfma_f32_16x16x32_bf16 v[122:125], v[172:175], v[196:199], v[122:125]
	v_mfma_f32_16x16x32_bf16 v[110:113], v[146:149], v[204:207], v[110:113]
	v_mfma_f32_16x16x32_bf16 v[106:109], v[172:175], v[204:207], v[106:109]
	v_mfma_f32_16x16x32_bf16 v[94:97], v[146:149], v[212:215], v[94:97]
	v_mfma_f32_16x16x32_bf16 v[90:93], v[172:175], v[212:215], v[90:93]
	v_mfma_f32_16x16x32_bf16 v[78:81], v[146:149], v[220:223], v[78:81]
	v_mfma_f32_16x16x32_bf16 v[74:77], v[172:175], v[220:223], v[74:77]
	v_mfma_f32_16x16x32_bf16 v[126:129], v[168:171], v[200:203], v[126:129]
	v_mfma_f32_16x16x32_bf16 v[122:125], v[176:179], v[200:203], v[122:125]
	v_mfma_f32_16x16x32_bf16 v[110:113], v[168:171], v[208:211], v[110:113]
	v_mfma_f32_16x16x32_bf16 v[106:109], v[176:179], v[208:211], v[106:109]
	v_mfma_f32_16x16x32_bf16 v[94:97], v[168:171], v[216:219], v[94:97]
	v_mfma_f32_16x16x32_bf16 v[90:93], v[176:179], v[216:219], v[90:93]
	v_mfma_f32_16x16x32_bf16 v[78:81], v[168:171], v[224:227], v[78:81]
	v_mfma_f32_16x16x32_bf16 v[74:77], v[176:179], v[224:227], v[74:77]
	s_setprio 0
	s_setprio 1
	v_mfma_f32_16x16x32_bf16 v[118:121], v[180:183], v[196:199], v[118:121]
	v_mfma_f32_16x16x32_bf16 v[114:117], v[188:191], v[196:199], v[114:117]
	v_mfma_f32_16x16x32_bf16 v[102:105], v[180:183], v[204:207], v[102:105]
	v_mfma_f32_16x16x32_bf16 v[98:101], v[188:191], v[204:207], v[98:101]
	v_mfma_f32_16x16x32_bf16 v[86:89], v[180:183], v[212:215], v[86:89]
	v_mfma_f32_16x16x32_bf16 v[82:85], v[188:191], v[212:215], v[82:85]
	v_mfma_f32_16x16x32_bf16 v[70:73], v[180:183], v[220:223], v[70:73]
	v_mfma_f32_16x16x32_bf16 v[66:69], v[188:191], v[220:223], v[66:69]
	v_mfma_f32_16x16x32_bf16 v[118:121], v[184:187], v[200:203], v[118:121]
	v_mfma_f32_16x16x32_bf16 v[114:117], v[192:195], v[200:203], v[114:117]
	v_mfma_f32_16x16x32_bf16 v[102:105], v[184:187], v[208:211], v[102:105]
	v_mfma_f32_16x16x32_bf16 v[98:101], v[192:195], v[208:211], v[98:101]
	v_mfma_f32_16x16x32_bf16 v[86:89], v[184:187], v[216:219], v[86:89]
	v_mfma_f32_16x16x32_bf16 v[82:85], v[192:195], v[216:219], v[82:85]
	v_mfma_f32_16x16x32_bf16 v[70:73], v[184:187], v[224:227], v[70:73]
	v_mfma_f32_16x16x32_bf16 v[66:69], v[192:195], v[224:227], v[66:69]
	s_setprio 0
	s_barrier
	s_add_i32 s21, s54, s43
	v_lshl_add_u64 v[228:229], s[62:63], 0, v[132:133]
	s_mov_b32 m0, s21
	ds_read_b128 v[196:199], v166 offset:16384
	ds_read_b128 v[200:203], v166 offset:17408
	ds_read_b128 v[204:207], v166 offset:18432
	ds_read_b128 v[208:211], v166 offset:19456
	ds_read_b128 v[212:215], v166 offset:20480
	ds_read_b128 v[216:219], v166 offset:21504
	ds_read_b128 v[220:223], v166 offset:22528
	ds_read_b128 v[224:227], v166 offset:23552
	global_load_lds_dwordx4 v[228:229], off
	s_add_i32 m0, s21, 0x2000
	v_lshl_add_u64 v[230:231], s[62:63], 0, v[136:137]
	s_add_u32 s62, s62, s16
	s_addc_u32 s63, s63, s17
	s_add_i32 s21, s55, s43
	global_load_lds_dwordx4 v[230:231], off
	v_lshl_add_u64 v[232:233], s[62:63], 0, v[132:133]
	s_mov_b32 m0, s21
	v_lshl_add_u64 v[234:235], s[62:63], 0, v[136:137]
	global_load_lds_dwordx4 v[232:233], off
	s_add_i32 m0, s21, 0x2000
	v_lshl_add_u64 v[236:237], s[36:37], 0, v[130:131]
	global_load_lds_dwordx4 v[234:235], off
	s_mov_b32 m0, s44
	v_lshl_add_u64 v[238:239], s[36:37], 0, v[134:135]
	global_load_lds_dwordx4 v[236:237], off
	s_mov_b32 m0, s45
	s_nop 0
	global_load_lds_dwordx4 v[238:239], off
	s_waitcnt vmcnt(8)
	s_waitcnt lgkmcnt(0)
	s_barrier
	s_setprio 1
	s_waitcnt lgkmcnt(0)
	v_mfma_f32_16x16x32_bf16 v[62:65], v[146:149], v[196:199], v[62:65]
	v_mfma_f32_16x16x32_bf16 v[58:61], v[172:175], v[196:199], v[58:61]
	v_mfma_f32_16x16x32_bf16 v[46:49], v[146:149], v[204:207], v[46:49]
	v_mfma_f32_16x16x32_bf16 v[42:45], v[172:175], v[204:207], v[42:45]
	v_mfma_f32_16x16x32_bf16 v[30:33], v[146:149], v[212:215], v[30:33]
	v_mfma_f32_16x16x32_bf16 v[26:29], v[172:175], v[212:215], v[26:29]
	v_mfma_f32_16x16x32_bf16 v[14:17], v[146:149], v[220:223], v[14:17]
	v_mfma_f32_16x16x32_bf16 v[10:13], v[172:175], v[220:223], v[10:13]
	v_mfma_f32_16x16x32_bf16 v[62:65], v[168:171], v[200:203], v[62:65]
	v_mfma_f32_16x16x32_bf16 v[58:61], v[176:179], v[200:203], v[58:61]
	v_mfma_f32_16x16x32_bf16 v[46:49], v[168:171], v[208:211], v[46:49]
	v_mfma_f32_16x16x32_bf16 v[42:45], v[176:179], v[208:211], v[42:45]
	v_mfma_f32_16x16x32_bf16 v[30:33], v[168:171], v[216:219], v[30:33]
	v_mfma_f32_16x16x32_bf16 v[26:29], v[176:179], v[216:219], v[26:29]
	v_mfma_f32_16x16x32_bf16 v[14:17], v[168:171], v[224:227], v[14:17]
	v_mfma_f32_16x16x32_bf16 v[10:13], v[176:179], v[224:227], v[10:13]
	s_setprio 0
	s_setprio 1
	v_mfma_f32_16x16x32_bf16 v[54:57], v[180:183], v[196:199], v[54:57]
	v_mfma_f32_16x16x32_bf16 v[50:53], v[188:191], v[196:199], v[50:53]
	v_mfma_f32_16x16x32_bf16 v[38:41], v[180:183], v[204:207], v[38:41]
	v_mfma_f32_16x16x32_bf16 v[34:37], v[188:191], v[204:207], v[34:37]
	v_mfma_f32_16x16x32_bf16 v[22:25], v[180:183], v[212:215], v[22:25]
	v_mfma_f32_16x16x32_bf16 v[18:21], v[188:191], v[212:215], v[18:21]
	v_mfma_f32_16x16x32_bf16 v[6:9], v[180:183], v[220:223], v[6:9]
	v_mfma_f32_16x16x32_bf16 v[2:5], v[188:191], v[220:223], v[2:5]
	v_mfma_f32_16x16x32_bf16 v[54:57], v[184:187], v[200:203], v[54:57]
	v_mfma_f32_16x16x32_bf16 v[50:53], v[192:195], v[200:203], v[50:53]
	v_mfma_f32_16x16x32_bf16 v[38:41], v[184:187], v[208:211], v[38:41]
	v_mfma_f32_16x16x32_bf16 v[34:37], v[192:195], v[208:211], v[34:37]
	v_mfma_f32_16x16x32_bf16 v[22:25], v[184:187], v[216:219], v[22:25]
	v_mfma_f32_16x16x32_bf16 v[18:21], v[192:195], v[216:219], v[18:21]
	v_mfma_f32_16x16x32_bf16 v[6:9], v[184:187], v[224:227], v[6:9]
	v_mfma_f32_16x16x32_bf16 v[2:5], v[192:195], v[224:227], v[2:5]
	s_setprio 0
	s_barrier
	s_add_i32 s21, 0, 0x18000
	v_add_u32_e32 v167, s21, v162
	s_add_i32 s61, 0, 0x1c000
	ds_read_b128 v[146:149], v167
	ds_read_b128 v[168:171], v167 offset:1024
	ds_read_b128 v[172:175], v167 offset:2048
	ds_read_b128 v[176:179], v167 offset:3072
	v_add_u32_e32 v167, s61, v162
	ds_read_b128 v[180:183], v167
	ds_read_b128 v[184:187], v167 offset:1024
	ds_read_b128 v[188:191], v167 offset:2048
	ds_read_b128 v[192:195], v167 offset:3072
	s_add_u32 s36, s36, 0x150000
	s_addc_u32 s37, s37, 0
	s_mov_b32 m0, s46
	s_nop 0
	ds_read_b128 v[196:199], v166 offset:32768
	ds_read_b128 v[200:203], v166 offset:33792
	ds_read_b128 v[204:207], v166 offset:34816
	ds_read_b128 v[208:211], v166 offset:35840
	ds_read_b128 v[212:215], v166 offset:36864
	ds_read_b128 v[216:219], v166 offset:37888
	ds_read_b128 v[220:223], v166 offset:38912
	ds_read_b128 v[224:227], v166 offset:39936
	global_load_lds_dwordx4 v130, s[36:37]
	v_lshl_add_u64 v[240:241], s[36:37], 0, v[134:135]
	s_mov_b32 m0, s47
	s_nop 0
	global_load_lds_dwordx4 v[240:241], off
	s_waitcnt vmcnt(8)
	s_waitcnt lgkmcnt(0)
	s_barrier
	s_setprio 1
	s_waitcnt lgkmcnt(0)
	v_mfma_f32_16x16x32_bf16 v[126:129], v[146:149], v[196:199], v[126:129]
	v_mfma_f32_16x16x32_bf16 v[122:125], v[172:175], v[196:199], v[122:125]
	v_mfma_f32_16x16x32_bf16 v[110:113], v[146:149], v[204:207], v[110:113]
	v_mfma_f32_16x16x32_bf16 v[106:109], v[172:175], v[204:207], v[106:109]
	v_mfma_f32_16x16x32_bf16 v[94:97], v[146:149], v[212:215], v[94:97]
	v_mfma_f32_16x16x32_bf16 v[90:93], v[172:175], v[212:215], v[90:93]
	v_mfma_f32_16x16x32_bf16 v[78:81], v[146:149], v[220:223], v[78:81]
	v_mfma_f32_16x16x32_bf16 v[74:77], v[172:175], v[220:223], v[74:77]
	v_mfma_f32_16x16x32_bf16 v[126:129], v[168:171], v[200:203], v[126:129]
	v_mfma_f32_16x16x32_bf16 v[122:125], v[176:179], v[200:203], v[122:125]
	v_mfma_f32_16x16x32_bf16 v[110:113], v[168:171], v[208:211], v[110:113]
	v_mfma_f32_16x16x32_bf16 v[106:109], v[176:179], v[208:211], v[106:109]
	v_mfma_f32_16x16x32_bf16 v[94:97], v[168:171], v[216:219], v[94:97]
	v_mfma_f32_16x16x32_bf16 v[90:93], v[176:179], v[216:219], v[90:93]
	v_mfma_f32_16x16x32_bf16 v[78:81], v[168:171], v[224:227], v[78:81]
	v_mfma_f32_16x16x32_bf16 v[74:77], v[176:179], v[224:227], v[74:77]
	s_setprio 0
	s_setprio 1
	v_mfma_f32_16x16x32_bf16 v[118:121], v[180:183], v[196:199], v[118:121]
	v_mfma_f32_16x16x32_bf16 v[114:117], v[188:191], v[196:199], v[114:117]
	v_mfma_f32_16x16x32_bf16 v[102:105], v[180:183], v[204:207], v[102:105]
	v_mfma_f32_16x16x32_bf16 v[98:101], v[188:191], v[204:207], v[98:101]
	v_mfma_f32_16x16x32_bf16 v[86:89], v[180:183], v[212:215], v[86:89]
	v_mfma_f32_16x16x32_bf16 v[82:85], v[188:191], v[212:215], v[82:85]
	v_mfma_f32_16x16x32_bf16 v[70:73], v[180:183], v[220:223], v[70:73]
	v_mfma_f32_16x16x32_bf16 v[66:69], v[188:191], v[220:223], v[66:69]
	v_mfma_f32_16x16x32_bf16 v[118:121], v[184:187], v[200:203], v[118:121]
	v_mfma_f32_16x16x32_bf16 v[114:117], v[192:195], v[200:203], v[114:117]
	v_mfma_f32_16x16x32_bf16 v[102:105], v[184:187], v[208:211], v[102:105]
	v_mfma_f32_16x16x32_bf16 v[98:101], v[192:195], v[208:211], v[98:101]
	v_mfma_f32_16x16x32_bf16 v[86:89], v[184:187], v[216:219], v[86:89]
	v_mfma_f32_16x16x32_bf16 v[82:85], v[192:195], v[216:219], v[82:85]
	v_mfma_f32_16x16x32_bf16 v[70:73], v[184:187], v[224:227], v[70:73]
	v_mfma_f32_16x16x32_bf16 v[66:69], v[192:195], v[224:227], v[66:69]
	s_setprio 0
	s_barrier
	s_add_i32 s21, s21, s43
	v_lshl_add_u64 v[228:229], v[228:229], 0, s[24:25]
	s_mov_b32 m0, s21
	ds_read_b128 v[196:199], v166 offset:49152
	ds_read_b128 v[200:203], v166 offset:50176
	ds_read_b128 v[204:207], v166 offset:51200
	ds_read_b128 v[208:211], v166 offset:52224
	ds_read_b128 v[212:215], v166 offset:53248
	ds_read_b128 v[216:219], v166 offset:54272
	ds_read_b128 v[220:223], v166 offset:55296
	ds_read_b128 v[224:227], v166 offset:56320
	global_load_lds_dwordx4 v[228:229], off
	v_lshl_add_u64 v[228:229], v[230:231], 0, s[24:25]
	s_add_i32 m0, s21, 0x2000
	s_add_i32 s21, s61, s43
	global_load_lds_dwordx4 v[228:229], off
	v_lshl_add_u64 v[228:229], v[232:233], 0, s[24:25]
	s_mov_b32 m0, s21
	s_nop 0
	global_load_lds_dwordx4 v[228:229], off
	v_lshl_add_u64 v[228:229], v[234:235], 0, s[24:25]
	s_add_i32 m0, s21, 0x2000
	s_nop 0
	global_load_lds_dwordx4 v[228:229], off
	v_lshl_add_u64 v[228:229], v[236:237], 0, s[24:25]
	s_mov_b32 m0, s49
	s_nop 0
	global_load_lds_dwordx4 v[228:229], off
	v_lshl_add_u64 v[228:229], v[238:239], 0, s[24:25]
	s_mov_b32 m0, s50
	s_nop 0
	global_load_lds_dwordx4 v[228:229], off
	s_waitcnt vmcnt(8)
	s_waitcnt lgkmcnt(0)
	s_barrier
	s_setprio 1
	s_waitcnt lgkmcnt(0)
	v_mfma_f32_16x16x32_bf16 v[62:65], v[146:149], v[196:199], v[62:65]
	v_mfma_f32_16x16x32_bf16 v[58:61], v[172:175], v[196:199], v[58:61]
	v_mfma_f32_16x16x32_bf16 v[46:49], v[146:149], v[204:207], v[46:49]
	v_mfma_f32_16x16x32_bf16 v[42:45], v[172:175], v[204:207], v[42:45]
	v_mfma_f32_16x16x32_bf16 v[30:33], v[146:149], v[212:215], v[30:33]
	v_mfma_f32_16x16x32_bf16 v[26:29], v[172:175], v[212:215], v[26:29]
	v_mfma_f32_16x16x32_bf16 v[14:17], v[146:149], v[220:223], v[14:17]
	v_mfma_f32_16x16x32_bf16 v[10:13], v[172:175], v[220:223], v[10:13]
	v_mfma_f32_16x16x32_bf16 v[62:65], v[168:171], v[200:203], v[62:65]
	v_mfma_f32_16x16x32_bf16 v[58:61], v[176:179], v[200:203], v[58:61]
	v_mfma_f32_16x16x32_bf16 v[46:49], v[168:171], v[208:211], v[46:49]
	v_mfma_f32_16x16x32_bf16 v[42:45], v[176:179], v[208:211], v[42:45]
	v_mfma_f32_16x16x32_bf16 v[30:33], v[168:171], v[216:219], v[30:33]
	v_mfma_f32_16x16x32_bf16 v[26:29], v[176:179], v[216:219], v[26:29]
	v_mfma_f32_16x16x32_bf16 v[14:17], v[168:171], v[224:227], v[14:17]
	v_mfma_f32_16x16x32_bf16 v[10:13], v[176:179], v[224:227], v[10:13]
	s_setprio 0
	s_setprio 1
	v_mfma_f32_16x16x32_bf16 v[54:57], v[180:183], v[196:199], v[54:57]
	v_mfma_f32_16x16x32_bf16 v[50:53], v[188:191], v[196:199], v[50:53]
	v_mfma_f32_16x16x32_bf16 v[38:41], v[180:183], v[204:207], v[38:41]
	v_mfma_f32_16x16x32_bf16 v[34:37], v[188:191], v[204:207], v[34:37]
	v_mfma_f32_16x16x32_bf16 v[22:25], v[180:183], v[212:215], v[22:25]
	v_mfma_f32_16x16x32_bf16 v[18:21], v[188:191], v[212:215], v[18:21]
	v_mfma_f32_16x16x32_bf16 v[6:9], v[180:183], v[220:223], v[6:9]
	v_mfma_f32_16x16x32_bf16 v[2:5], v[188:191], v[220:223], v[2:5]
	v_mfma_f32_16x16x32_bf16 v[54:57], v[184:187], v[200:203], v[54:57]
	v_mfma_f32_16x16x32_bf16 v[50:53], v[192:195], v[200:203], v[50:53]
	v_mfma_f32_16x16x32_bf16 v[38:41], v[184:187], v[208:211], v[38:41]
	v_mfma_f32_16x16x32_bf16 v[34:37], v[192:195], v[208:211], v[34:37]
	v_mfma_f32_16x16x32_bf16 v[22:25], v[184:187], v[216:219], v[22:25]
	v_mfma_f32_16x16x32_bf16 v[18:21], v[192:195], v[216:219], v[18:21]
	v_mfma_f32_16x16x32_bf16 v[6:9], v[184:187], v[224:227], v[6:9]
	v_mfma_f32_16x16x32_bf16 v[2:5], v[192:195], v[224:227], v[2:5]
	s_setprio 0
	s_barrier
	s_add_u32 s34, s34, 0x100
	s_addc_u32 s35, s35, 0
	s_add_u32 s10, s10, 0x100
	s_addc_u32 s20, s20, 0
	s_cmp_ge_i32 s60, s51
	s_mov_b32 s21, s60
	s_cbranch_scc0 .LBB0_502

.LBB0_516:
	s_mov_b64 s[14:15], 0x80
	s_lshl_b32 s5, s5, 5
	s_add_i32 m0, s38, 0x18000
	v_lshl_add_u64 v[8:9], v[8:9], 0, s[14:15]
	s_lshl_b32 s10, s3, 13
	s_and_b32 s5, s5, 0x60
	s_waitcnt vmcnt(2)
	s_barrier
	global_load_lds_dwordx4 v[8:9], off
	v_lshl_add_u64 v[6:7], v[6:7], 0, s[14:15]
	s_add_i32 m0, s38, 0x1a000
	s_add_i32 s43, s38, 0x8000
	s_add_i32 s44, s38, 0xa000
	global_load_lds_dwordx4 v[6:7], off
	v_lshl_add_u64 v[2:3], v[2:3], 0, s[14:15]
	s_mov_b32 m0, s43
	s_add_u32 s16, s26, 0x40080
	global_load_lds_dwordx4 v[2:3], off
	v_lshl_add_u64 v[2:3], v[4:5], 0, s[14:15]
	s_mov_b32 m0, s44
	s_addc_u32 s17, s27, 0
	global_load_lds_dwordx4 v[2:3], off
	s_add_i32 m0, s38, 0x1c000
	s_nop 0
	global_load_lds_dwordx4 v132, s[16:17]
	s_nop 0
	s_add_i32 m0, s38, 0x1e000
	s_cmpk_lt_u32 s4, 0x100
	global_load_lds_dwordx4 v136, s[16:17]
	v_lshlrev_b32_e32 v3, 2, v152
	v_lshl_or_b32 v2, v152, 6, v153
	v_and_b32_e32 v3, 32, v3
	s_waitcnt vmcnt(6)
	v_lshl_or_b32 v155, s3, 6, v152
	v_bitop3_b32 v2, v2, s10, v3 bitop3:0xde
	v_lshl_or_b32 v152, s5, 7, v154
	s_cselect_b64 s[16:17], -1, 0
	s_add_i32 s46, 0, 0x10000
	s_add_i32 s47, 0, 0x14000
	s_sext_i32_i8 s50, s2
	s_ashr_i32 s45, s11, 31
	v_or_b32_e32 v151, s5, v151
	s_waitcnt vmcnt(0)
	v_add3_u32 v138, v10, v1, v150
	v_mov_b32_e32 v139, v133
	v_add3_u32 v140, v11, v1, v150
	v_mov_b32_e32 v141, v133
	v_mov_b64_e32 v[142:143], 0x200
	v_mov_b64_e32 v[144:145], 0x1ff
	v_add_u32_e32 v1, s46, v152
	v_add_u32_e32 v150, s47, v152
	v_add_u32_e32 v153, 0, v2
	s_barrier
	s_branch .LBB0_519

.LBB0_528:
	ds_read_b128 v[146:149], v1
	ds_read_b128 v[156:159], v1 offset:1024
	ds_read_b128 v[160:163], v1 offset:2048
	ds_read_b128 v[164:167], v1 offset:3072
	ds_read_b128 v[168:171], v150
	ds_read_b128 v[172:175], v150 offset:1024
	ds_read_b128 v[176:179], v150 offset:2048
	ds_read_b128 v[180:183], v150 offset:3072
	s_add_u32 s26, s4, 0xffeb0080
	s_addc_u32 s27, s5, -1
	s_cmp_eq_u32 s51, 12
	s_cselect_b32 s29, s23, s27
	s_cselect_b32 s28, s22, s26
	s_cselect_b32 s27, s10, s21
	s_cselect_b32 s26, s19, s20
	s_nop 0
	s_add_i32 m0, s38, 0xc000
	ds_read_b128 v[184:187], v153
	ds_read_b128 v[188:191], v153 offset:1024
	ds_read_b128 v[192:195], v153 offset:2048
	ds_read_b128 v[196:199], v153 offset:3072
	ds_read_b128 v[200:203], v153 offset:4096
	ds_read_b128 v[204:207], v153 offset:5120
	ds_read_b128 v[208:211], v153 offset:6144
	ds_read_b128 v[212:215], v153 offset:7168
	global_load_lds_dwordx4 v138, s[4:5]
	s_nop 0
	s_add_i32 m0, s38, 0xe000
	s_nop 0
	global_load_lds_dwordx4 v140, s[4:5]
	s_waitcnt vmcnt(8)
	s_waitcnt lgkmcnt(0)
	s_barrier
	s_setprio 1
	s_waitcnt lgkmcnt(0)
	v_mfma_f32_16x16x32_bf16 v[126:129], v[146:149], v[184:187], v[126:129]
	v_mfma_f32_16x16x32_bf16 v[122:125], v[160:163], v[184:187], v[122:125]
	v_mfma_f32_16x16x32_bf16 v[110:113], v[146:149], v[192:195], v[110:113]
	v_mfma_f32_16x16x32_bf16 v[106:109], v[160:163], v[192:195], v[106:109]
	v_mfma_f32_16x16x32_bf16 v[94:97], v[146:149], v[200:203], v[94:97]
	v_mfma_f32_16x16x32_bf16 v[90:93], v[160:163], v[200:203], v[90:93]
	v_mfma_f32_16x16x32_bf16 v[78:81], v[146:149], v[208:211], v[78:81]
	v_mfma_f32_16x16x32_bf16 v[74:77], v[160:163], v[208:211], v[74:77]
	v_mfma_f32_16x16x32_bf16 v[126:129], v[156:159], v[188:191], v[126:129]
	v_mfma_f32_16x16x32_bf16 v[122:125], v[164:167], v[188:191], v[122:125]
	v_mfma_f32_16x16x32_bf16 v[110:113], v[156:159], v[196:199], v[110:113]
	v_mfma_f32_16x16x32_bf16 v[106:109], v[164:167], v[196:199], v[106:109]
	v_mfma_f32_16x16x32_bf16 v[94:97], v[156:159], v[204:207], v[94:97]
	v_mfma_f32_16x16x32_bf16 v[90:93], v[164:167], v[204:207], v[90:93]
	v_mfma_f32_16x16x32_bf16 v[78:81], v[156:159], v[212:215], v[78:81]
	v_mfma_f32_16x16x32_bf16 v[74:77], v[164:167], v[212:215], v[74:77]
	s_setprio 0
	s_setprio 1
	v_mfma_f32_16x16x32_bf16 v[118:121], v[168:171], v[184:187], v[118:121]
	v_mfma_f32_16x16x32_bf16 v[114:117], v[176:179], v[184:187], v[114:117]
	v_mfma_f32_16x16x32_bf16 v[102:105], v[168:171], v[192:195], v[102:105]
	v_mfma_f32_16x16x32_bf16 v[98:101], v[176:179], v[192:195], v[98:101]
	v_mfma_f32_16x16x32_bf16 v[86:89], v[168:171], v[200:203], v[86:89]
	v_mfma_f32_16x16x32_bf16 v[82:85], v[176:179], v[200:203], v[82:85]
	v_mfma_f32_16x16x32_bf16 v[70:73], v[168:171], v[208:211], v[70:73]
	v_mfma_f32_16x16x32_bf16 v[66:69], v[176:179], v[208:211], v[66:69]
	v_mfma_f32_16x16x32_bf16 v[118:121], v[172:175], v[188:191], v[118:121]
	v_mfma_f32_16x16x32_bf16 v[114:117], v[180:183], v[188:191], v[114:117]
	v_mfma_f32_16x16x32_bf16 v[102:105], v[172:175], v[196:199], v[102:105]
	v_mfma_f32_16x16x32_bf16 v[98:101], v[180:183], v[196:199], v[98:101]
	v_mfma_f32_16x16x32_bf16 v[86:89], v[172:175], v[204:207], v[86:89]
	v_mfma_f32_16x16x32_bf16 v[82:85], v[180:183], v[204:207], v[82:85]
	v_mfma_f32_16x16x32_bf16 v[70:73], v[172:175], v[212:215], v[70:73]
	v_mfma_f32_16x16x32_bf16 v[66:69], v[180:183], v[212:215], v[66:69]
	s_setprio 0
	s_barrier
	s_add_i32 s52, s46, s31
	v_lshl_add_u64 v[216:217], s[26:27], 0, v[132:133]
	s_mov_b32 m0, s52
	ds_read_b128 v[184:187], v153 offset:16384
	ds_read_b128 v[188:191], v153 offset:17408
	ds_read_b128 v[192:195], v153 offset:18432
	ds_read_b128 v[196:199], v153 offset:19456
	ds_read_b128 v[200:203], v153 offset:20480
	ds_read_b128 v[204:207], v153 offset:21504
	ds_read_b128 v[208:211], v153 offset:22528
	ds_read_b128 v[212:215], v153 offset:23552
	global_load_lds_dwordx4 v[216:217], off
	s_add_i32 m0, s52, 0x2000
	s_add_u32 s52, s26, 0x40000
	v_lshl_add_u64 v[218:219], s[26:27], 0, v[136:137]
	s_addc_u32 s53, s27, 0
	s_add_i32 s54, s47, s31
	global_load_lds_dwordx4 v[218:219], off
	s_nop 0
	s_mov_b32 m0, s54
	v_lshl_add_u64 v[222:223], s[28:29], 0, v[134:135]
	global_load_lds_dwordx4 v132, s[52:53]
	s_nop 0
	s_add_i32 m0, s54, 0x2000
	s_nop 0
	global_load_lds_dwordx4 v136, s[52:53]
	v_lshl_add_u64 v[220:221], s[28:29], 0, v[130:131]
	s_mov_b32 m0, s38
	s_nop 0
	global_load_lds_dwordx4 v[220:221], off
	s_mov_b32 m0, s39
	s_nop 0
	global_load_lds_dwordx4 v[222:223], off
	s_waitcnt vmcnt(8)
	s_waitcnt lgkmcnt(0)
	s_barrier
	s_setprio 1
	s_waitcnt lgkmcnt(0)
	v_mfma_f32_16x16x32_bf16 v[62:65], v[146:149], v[184:187], v[62:65]
	v_mfma_f32_16x16x32_bf16 v[58:61], v[160:163], v[184:187], v[58:61]
	v_mfma_f32_16x16x32_bf16 v[46:49], v[146:149], v[192:195], v[46:49]
	v_mfma_f32_16x16x32_bf16 v[42:45], v[160:163], v[192:195], v[42:45]
	v_mfma_f32_16x16x32_bf16 v[30:33], v[146:149], v[200:203], v[30:33]
	v_mfma_f32_16x16x32_bf16 v[26:29], v[160:163], v[200:203], v[26:29]
	v_mfma_f32_16x16x32_bf16 v[14:17], v[146:149], v[208:211], v[14:17]
	v_mfma_f32_16x16x32_bf16 v[10:13], v[160:163], v[208:211], v[10:13]
	v_mfma_f32_16x16x32_bf16 v[62:65], v[156:159], v[188:191], v[62:65]
	v_mfma_f32_16x16x32_bf16 v[58:61], v[164:167], v[188:191], v[58:61]
	v_mfma_f32_16x16x32_bf16 v[46:49], v[156:159], v[196:199], v[46:49]
	v_mfma_f32_16x16x32_bf16 v[42:45], v[164:167], v[196:199], v[42:45]
	v_mfma_f32_16x16x32_bf16 v[30:33], v[156:159], v[204:207], v[30:33]
	v_mfma_f32_16x16x32_bf16 v[26:29], v[164:167], v[204:207], v[26:29]
	v_mfma_f32_16x16x32_bf16 v[14:17], v[156:159], v[212:215], v[14:17]
	v_mfma_f32_16x16x32_bf16 v[10:13], v[164:167], v[212:215], v[10:13]
	s_setprio 0
	s_setprio 1
	v_mfma_f32_16x16x32_bf16 v[54:57], v[168:171], v[184:187], v[54:57]
	v_mfma_f32_16x16x32_bf16 v[50:53], v[176:179], v[184:187], v[50:53]
	v_mfma_f32_16x16x32_bf16 v[38:41], v[168:171], v[192:195], v[38:41]
	v_mfma_f32_16x16x32_bf16 v[34:37], v[176:179], v[192:195], v[34:37]
	v_mfma_f32_16x16x32_bf16 v[22:25], v[168:171], v[200:203], v[22:25]
	v_mfma_f32_16x16x32_bf16 v[18:21], v[176:179], v[200:203], v[18:21]
	v_mfma_f32_16x16x32_bf16 v[6:9], v[168:171], v[208:211], v[6:9]
	v_mfma_f32_16x16x32_bf16 v[2:5], v[176:179], v[208:211], v[2:5]
	v_mfma_f32_16x16x32_bf16 v[54:57], v[172:175], v[188:191], v[54:57]
	v_mfma_f32_16x16x32_bf16 v[50:53], v[180:183], v[188:191], v[50:53]
	v_mfma_f32_16x16x32_bf16 v[38:41], v[172:175], v[196:199], v[38:41]
	v_mfma_f32_16x16x32_bf16 v[34:37], v[180:183], v[196:199], v[34:37]
	v_mfma_f32_16x16x32_bf16 v[22:25], v[172:175], v[204:207], v[22:25]
	v_mfma_f32_16x16x32_bf16 v[18:21], v[180:183], v[204:207], v[18:21]
	v_mfma_f32_16x16x32_bf16 v[6:9], v[172:175], v[212:215], v[6:9]
	v_mfma_f32_16x16x32_bf16 v[2:5], v[180:183], v[212:215], v[2:5]
	s_setprio 0
	s_barrier
	s_add_i32 s52, 0, 0x18000
	v_add_u32_e32 v154, s52, v152
	s_add_i32 s53, 0, 0x1c000
	ds_read_b128 v[146:149], v154
	ds_read_b128 v[156:159], v154 offset:1024
	ds_read_b128 v[160:163], v154 offset:2048
	ds_read_b128 v[164:167], v154 offset:3072
	v_add_u32_e32 v154, s53, v152
	ds_read_b128 v[168:171], v154
	ds_read_b128 v[172:175], v154 offset:1024
	ds_read_b128 v[176:179], v154 offset:2048
	ds_read_b128 v[180:183], v154 offset:3072
	s_add_u32 s28, s28, 0x150000
	s_addc_u32 s29, s29, 0
	s_mov_b32 m0, s40
	s_nop 0
	ds_read_b128 v[184:187], v153 offset:32768
	ds_read_b128 v[188:191], v153 offset:33792
	ds_read_b128 v[192:195], v153 offset:34816
	ds_read_b128 v[196:199], v153 offset:35840
	ds_read_b128 v[200:203], v153 offset:36864
	ds_read_b128 v[204:207], v153 offset:37888
	ds_read_b128 v[208:211], v153 offset:38912
	ds_read_b128 v[212:215], v153 offset:39936
	global_load_lds_dwordx4 v130, s[28:29]
	v_lshl_add_u64 v[224:225], s[28:29], 0, v[134:135]
	s_mov_b32 m0, s41
	s_nop 0
	global_load_lds_dwordx4 v[224:225], off
	s_waitcnt vmcnt(8)
	s_waitcnt lgkmcnt(0)
	s_barrier
	s_setprio 1
	s_waitcnt lgkmcnt(0)
	v_mfma_f32_16x16x32_bf16 v[126:129], v[146:149], v[184:187], v[126:129]
	v_mfma_f32_16x16x32_bf16 v[122:125], v[160:163], v[184:187], v[122:125]
	v_mfma_f32_16x16x32_bf16 v[110:113], v[146:149], v[192:195], v[110:113]
	v_mfma_f32_16x16x32_bf16 v[106:109], v[160:163], v[192:195], v[106:109]
	v_mfma_f32_16x16x32_bf16 v[94:97], v[146:149], v[200:203], v[94:97]
	v_mfma_f32_16x16x32_bf16 v[90:93], v[160:163], v[200:203], v[90:93]
	v_mfma_f32_16x16x32_bf16 v[78:81], v[146:149], v[208:211], v[78:81]
	v_mfma_f32_16x16x32_bf16 v[74:77], v[160:163], v[208:211], v[74:77]
	v_mfma_f32_16x16x32_bf16 v[126:129], v[156:159], v[188:191], v[126:129]
	v_mfma_f32_16x16x32_bf16 v[122:125], v[164:167], v[188:191], v[122:125]
	v_mfma_f32_16x16x32_bf16 v[110:113], v[156:159], v[196:199], v[110:113]
	v_mfma_f32_16x16x32_bf16 v[106:109], v[164:167], v[196:199], v[106:109]
	v_mfma_f32_16x16x32_bf16 v[94:97], v[156:159], v[204:207], v[94:97]
	v_mfma_f32_16x16x32_bf16 v[90:93], v[164:167], v[204:207], v[90:93]
	v_mfma_f32_16x16x32_bf16 v[78:81], v[156:159], v[212:215], v[78:81]
	v_mfma_f32_16x16x32_bf16 v[74:77], v[164:167], v[212:215], v[74:77]
	s_setprio 0
	s_setprio 1
	v_mfma_f32_16x16x32_bf16 v[118:121], v[168:171], v[184:187], v[118:121]
	v_mfma_f32_16x16x32_bf16 v[114:117], v[176:179], v[184:187], v[114:117]
	v_mfma_f32_16x16x32_bf16 v[102:105], v[168:171], v[192:195], v[102:105]
	v_mfma_f32_16x16x32_bf16 v[98:101], v[176:179], v[192:195], v[98:101]
	v_mfma_f32_16x16x32_bf16 v[86:89], v[168:171], v[200:203], v[86:89]
	v_mfma_f32_16x16x32_bf16 v[82:85], v[176:179], v[200:203], v[82:85]
	v_mfma_f32_16x16x32_bf16 v[70:73], v[168:171], v[208:211], v[70:73]
	v_mfma_f32_16x16x32_bf16 v[66:69], v[176:179], v[208:211], v[66:69]
	v_mfma_f32_16x16x32_bf16 v[118:121], v[172:175], v[188:191], v[118:121]
	v_mfma_f32_16x16x32_bf16 v[114:117], v[180:183], v[188:191], v[114:117]
	v_mfma_f32_16x16x32_bf16 v[102:105], v[172:175], v[196:199], v[102:105]
	v_mfma_f32_16x16x32_bf16 v[98:101], v[180:183], v[196:199], v[98:101]
	v_mfma_f32_16x16x32_bf16 v[86:89], v[172:175], v[204:207], v[86:89]
	v_mfma_f32_16x16x32_bf16 v[82:85], v[180:183], v[204:207], v[82:85]
	v_mfma_f32_16x16x32_bf16 v[70:73], v[172:175], v[212:215], v[70:73]
	v_mfma_f32_16x16x32_bf16 v[66:69], v[180:183], v[212:215], v[66:69]
	s_setprio 0
	s_barrier
	s_add_i32 s28, s52, s31
	v_lshl_add_u64 v[216:217], v[216:217], 0, s[14:15]
	s_mov_b32 m0, s28
	ds_read_b128 v[184:187], v153 offset:49152
	ds_read_b128 v[188:191], v153 offset:50176
	ds_read_b128 v[192:195], v153 offset:51200
	ds_read_b128 v[196:199], v153 offset:52224
	ds_read_b128 v[200:203], v153 offset:53248
	ds_read_b128 v[204:207], v153 offset:54272
	ds_read_b128 v[208:211], v153 offset:55296
	ds_read_b128 v[212:215], v153 offset:56320
	global_load_lds_dwordx4 v[216:217], off
	s_add_i32 m0, s28, 0x2000
	s_add_u32 s26, s26, 0x40080
	v_lshl_add_u64 v[216:217], v[218:219], 0, s[14:15]
	s_addc_u32 s27, s27, 0
	s_add_i32 s28, s53, s31
	global_load_lds_dwordx4 v[216:217], off
	s_nop 0
	s_mov_b32 m0, s28
	s_nop 0
	global_load_lds_dwordx4 v132, s[26:27]
	s_nop 0
	s_add_i32 m0, s28, 0x2000
	s_nop 0
	global_load_lds_dwordx4 v136, s[26:27]
	v_lshl_add_u64 v[216:217], v[220:221], 0, s[14:15]
	s_mov_b32 m0, s43
	s_nop 0
	global_load_lds_dwordx4 v[216:217], off
	v_lshl_add_u64 v[216:217], v[222:223], 0, s[14:15]
	s_mov_b32 m0, s44
	s_nop 0
	global_load_lds_dwordx4 v[216:217], off
	s_waitcnt vmcnt(8)
	s_waitcnt lgkmcnt(0)
	s_barrier
	s_setprio 1
	s_waitcnt lgkmcnt(0)
	v_mfma_f32_16x16x32_bf16 v[62:65], v[146:149], v[184:187], v[62:65]
	v_mfma_f32_16x16x32_bf16 v[58:61], v[160:163], v[184:187], v[58:61]
	v_mfma_f32_16x16x32_bf16 v[46:49], v[146:149], v[192:195], v[46:49]
	v_mfma_f32_16x16x32_bf16 v[42:45], v[160:163], v[192:195], v[42:45]
	v_mfma_f32_16x16x32_bf16 v[30:33], v[146:149], v[200:203], v[30:33]
	v_mfma_f32_16x16x32_bf16 v[26:29], v[160:163], v[200:203], v[26:29]
	v_mfma_f32_16x16x32_bf16 v[14:17], v[146:149], v[208:211], v[14:17]
	v_mfma_f32_16x16x32_bf16 v[10:13], v[160:163], v[208:211], v[10:13]
	v_mfma_f32_16x16x32_bf16 v[62:65], v[156:159], v[188:191], v[62:65]
	v_mfma_f32_16x16x32_bf16 v[58:61], v[164:167], v[188:191], v[58:61]
	v_mfma_f32_16x16x32_bf16 v[46:49], v[156:159], v[196:199], v[46:49]
	v_mfma_f32_16x16x32_bf16 v[42:45], v[164:167], v[196:199], v[42:45]
	v_mfma_f32_16x16x32_bf16 v[30:33], v[156:159], v[204:207], v[30:33]
	v_mfma_f32_16x16x32_bf16 v[26:29], v[164:167], v[204:207], v[26:29]
	v_mfma_f32_16x16x32_bf16 v[14:17], v[156:159], v[212:215], v[14:17]
	v_mfma_f32_16x16x32_bf16 v[10:13], v[164:167], v[212:215], v[10:13]
	s_setprio 0
	s_setprio 1
	v_mfma_f32_16x16x32_bf16 v[54:57], v[168:171], v[184:187], v[54:57]
	v_mfma_f32_16x16x32_bf16 v[50:53], v[176:179], v[184:187], v[50:53]
	v_mfma_f32_16x16x32_bf16 v[38:41], v[168:171], v[192:195], v[38:41]
	v_mfma_f32_16x16x32_bf16 v[34:37], v[176:179], v[192:195], v[34:37]
	v_mfma_f32_16x16x32_bf16 v[22:25], v[168:171], v[200:203], v[22:25]
	v_mfma_f32_16x16x32_bf16 v[18:21], v[176:179], v[200:203], v[18:21]
	v_mfma_f32_16x16x32_bf16 v[6:9], v[168:171], v[208:211], v[6:9]
	v_mfma_f32_16x16x32_bf16 v[2:5], v[176:179], v[208:211], v[2:5]
	v_mfma_f32_16x16x32_bf16 v[54:57], v[172:175], v[188:191], v[54:57]
	v_mfma_f32_16x16x32_bf16 v[50:53], v[180:183], v[188:191], v[50:53]
	v_mfma_f32_16x16x32_bf16 v[38:41], v[172:175], v[196:199], v[38:41]
	v_mfma_f32_16x16x32_bf16 v[34:37], v[180:183], v[196:199], v[34:37]
	v_mfma_f32_16x16x32_bf16 v[22:25], v[172:175], v[204:207], v[22:25]
	v_mfma_f32_16x16x32_bf16 v[18:21], v[180:183], v[204:207], v[18:21]
	v_mfma_f32_16x16x32_bf16 v[6:9], v[172:175], v[212:215], v[6:9]
	v_mfma_f32_16x16x32_bf16 v[2:5], v[180:183], v[212:215], v[2:5]
	s_setprio 0
	s_barrier
	s_add_i32 s51, s51, 2
	s_add_u32 s4, s4, 0x100
	s_addc_u32 s5, s5, 0
	s_add_u32 s20, s20, 0x100
	s_addc_u32 s21, s21, 0
	s_cmp_gt_u32 s51, 13
	s_cbranch_scc0 .LBB0_528
	s_and_b64 vcc, exec, s[16:17]
	s_cbranch_vccz .LBB0_531
	s_barrier

.LBB0_566:
	s_add_u32 s8, s2, 0xa900000
	s_addc_u32 s9, s3, 0
	s_lshl_b32 s2, s12, 5
	s_mov_b64 s[12:13], 0x80
	s_and_b32 s17, s2, 0x60
	s_add_i32 m0, s25, 0x18000
	v_lshl_add_u64 v[8:9], v[8:9], 0, s[12:13]
	s_lshl_b32 s16, s15, 13
	s_lshl_b32 s18, s17, 7
	s_waitcnt vmcnt(2)
	s_barrier
	global_load_lds_dwordx4 v[8:9], off
	v_lshl_add_u64 v[4:5], v[4:5], 0, s[12:13]
	s_add_i32 m0, s25, 0x1a000
	s_add_i32 s52, s25, 0x8000
	s_add_i32 s53, s25, 0xa000
	global_load_lds_dwordx4 v[4:5], off
	v_lshl_add_u64 v[2:3], v[2:3], 0, s[12:13]
	s_mov_b32 m0, s52
	s_add_u32 s2, s38, 0x40080
	global_load_lds_dwordx4 v[2:3], off
	v_lshl_add_u64 v[2:3], v[6:7], 0, s[12:13]
	s_mov_b32 m0, s53
	s_addc_u32 s3, s39, 0
	global_load_lds_dwordx4 v[2:3], off
	s_add_i32 m0, s25, 0x1c000
	s_nop 0
	global_load_lds_dwordx4 v132, s[2:3]
	s_nop 0
	s_add_i32 m0, s25, 0x1e000
	v_lshlrev_b32_e32 v4, 2, v10
	global_load_lds_dwordx4 v136, s[2:3]
	v_and_b32_e32 v2, 15, v10
	v_lshlrev_b32_e32 v3, 1, v14
	v_lshlrev_b32_e32 v5, 6, v10
	s_movk_i32 s2, 0x3c0
	v_lshl_or_b32 v1, s15, 6, v2
	v_lshl_or_b32 v2, v2, 6, v3
	v_and_b32_e32 v4, 32, v4
	v_and_or_b32 v3, v5, s2, v3
	v_bitop3_b32 v146, s18, v3, v4 bitop3:0xf6
	v_lshlrev_b32_e32 v3, 8, v10
	v_bitop3_b32 v2, v2, s16, v4 bitop3:0xde
	v_and_b32_e32 v3, 0x38000, v3
	v_lshlrev_b32_e32 v4, 11, v13
	v_or3_b32 v3, v11, v3, v4
	s_waitcnt vmcnt(0)
	v_add_u32_e32 v138, v3, v12
	v_lshlrev_b32_e32 v3, 4, v15
	s_waitcnt vmcnt(6)
	s_cmpk_lt_u32 s10, 0x100
	v_and_b32_e32 v3, 0x78000, v3
	s_sext_i32_i8 s61, s14
	s_cselect_b64 s[14:15], -1, 0
	v_or3_b32 v3, v11, v3, v4
	s_add_i32 s55, 0, 0x10000
	s_add_i32 s56, 0, 0x14000
	s_ashr_i32 s54, s11, 31
	v_or_b32_e32 v147, s17, v14
	v_mov_b32_e32 v139, v133
	v_add_u32_e32 v140, v3, v12
	v_mov_b32_e32 v141, v133
	v_mov_b64_e32 v[142:143], 0x200
	v_mov_b64_e32 v[144:145], 0x1ff
	v_add_u32_e32 v148, s55, v146
	v_add_u32_e32 v149, s56, v146
	v_add_u32_e32 v150, 0, v2
	s_mov_b32 s57, 0x40000
	s_mov_b64 s[16:17], 0x48000
	s_mov_b32 s58, 0x48000
	s_mov_b64 s[18:19], 0x50000
	s_mov_b32 s59, 0x50000
	s_mov_b64 s[22:23], 0x58000
	s_mov_b32 s60, 0x58000
	s_barrier
	s_branch .LBB0_569

.LBB0_576:
	ds_read_b128 v[152:155], v148
	ds_read_b128 v[156:159], v148 offset:1024
	ds_read_b128 v[160:163], v148 offset:2048
	ds_read_b128 v[164:167], v148 offset:3072
	ds_read_b128 v[168:171], v149
	ds_read_b128 v[172:175], v149 offset:1024
	ds_read_b128 v[176:179], v149 offset:2048
	ds_read_b128 v[180:183], v149 offset:3072
	s_add_u32 s38, s36, 0xfffc0080
	s_addc_u32 s39, s37, -1
	s_cmp_eq_u32 s63, 12
	s_cselect_b32 s41, s10, s39
	s_cselect_b32 s40, s20, s38
	s_cselect_b32 s39, s21, s62
	s_cselect_b32 s38, s27, s29
	s_nop 0
	s_add_i32 m0, s25, 0xc000
	ds_read_b128 v[184:187], v150
	ds_read_b128 v[188:191], v150 offset:1024
	ds_read_b128 v[192:195], v150 offset:2048
	ds_read_b128 v[196:199], v150 offset:3072
	ds_read_b128 v[200:203], v150 offset:4096
	ds_read_b128 v[204:207], v150 offset:5120
	ds_read_b128 v[208:211], v150 offset:6144
	ds_read_b128 v[212:215], v150 offset:7168
	global_load_lds_dwordx4 v138, s[36:37]
	s_nop 0
	s_add_i32 m0, s25, 0xe000
	s_nop 0
	global_load_lds_dwordx4 v140, s[36:37]
	s_waitcnt vmcnt(8)
	s_waitcnt lgkmcnt(0)
	s_barrier
	s_setprio 1
	s_waitcnt lgkmcnt(0)
	v_mfma_f32_16x16x32_bf16 v[126:129], v[152:155], v[184:187], v[126:129]
	v_mfma_f32_16x16x32_bf16 v[122:125], v[160:163], v[184:187], v[122:125]
	v_mfma_f32_16x16x32_bf16 v[118:121], v[152:155], v[192:195], v[118:121]
	v_mfma_f32_16x16x32_bf16 v[114:117], v[160:163], v[192:195], v[114:117]
	v_mfma_f32_16x16x32_bf16 v[102:105], v[152:155], v[200:203], v[102:105]
	v_mfma_f32_16x16x32_bf16 v[98:101], v[160:163], v[200:203], v[98:101]
	v_mfma_f32_16x16x32_bf16 v[86:89], v[152:155], v[208:211], v[86:89]
	v_mfma_f32_16x16x32_bf16 v[82:85], v[160:163], v[208:211], v[82:85]
	v_mfma_f32_16x16x32_bf16 v[126:129], v[156:159], v[188:191], v[126:129]
	v_mfma_f32_16x16x32_bf16 v[122:125], v[164:167], v[188:191], v[122:125]
	v_mfma_f32_16x16x32_bf16 v[118:121], v[156:159], v[196:199], v[118:121]
	v_mfma_f32_16x16x32_bf16 v[114:117], v[164:167], v[196:199], v[114:117]
	v_mfma_f32_16x16x32_bf16 v[102:105], v[156:159], v[204:207], v[102:105]
	v_mfma_f32_16x16x32_bf16 v[98:101], v[164:167], v[204:207], v[98:101]
	v_mfma_f32_16x16x32_bf16 v[86:89], v[156:159], v[212:215], v[86:89]
	v_mfma_f32_16x16x32_bf16 v[82:85], v[164:167], v[212:215], v[82:85]
	s_setprio 0
	s_setprio 1
	v_mfma_f32_16x16x32_bf16 v[110:113], v[168:171], v[184:187], v[110:113]
	v_mfma_f32_16x16x32_bf16 v[106:109], v[176:179], v[184:187], v[106:109]
	v_mfma_f32_16x16x32_bf16 v[94:97], v[168:171], v[192:195], v[94:97]
	v_mfma_f32_16x16x32_bf16 v[90:93], v[176:179], v[192:195], v[90:93]
	v_mfma_f32_16x16x32_bf16 v[78:81], v[168:171], v[200:203], v[78:81]
	v_mfma_f32_16x16x32_bf16 v[74:77], v[176:179], v[200:203], v[74:77]
	v_mfma_f32_16x16x32_bf16 v[70:73], v[168:171], v[208:211], v[70:73]
	v_mfma_f32_16x16x32_bf16 v[66:69], v[176:179], v[208:211], v[66:69]
	v_mfma_f32_16x16x32_bf16 v[110:113], v[172:175], v[188:191], v[110:113]
	v_mfma_f32_16x16x32_bf16 v[106:109], v[180:183], v[188:191], v[106:109]
	v_mfma_f32_16x16x32_bf16 v[94:97], v[172:175], v[196:199], v[94:97]
	v_mfma_f32_16x16x32_bf16 v[90:93], v[180:183], v[196:199], v[90:93]
	v_mfma_f32_16x16x32_bf16 v[78:81], v[172:175], v[204:207], v[78:81]
	v_mfma_f32_16x16x32_bf16 v[74:77], v[180:183], v[204:207], v[74:77]
	v_mfma_f32_16x16x32_bf16 v[70:73], v[172:175], v[212:215], v[70:73]
	v_mfma_f32_16x16x32_bf16 v[66:69], v[180:183], v[212:215], v[66:69]
	s_setprio 0
	s_barrier
	s_add_i32 s64, s55, s47
	v_lshl_add_u64 v[216:217], s[38:39], 0, v[132:133]
	s_mov_b32 m0, s64
	ds_read_b128 v[184:187], v150 offset:16384
	ds_read_b128 v[188:191], v150 offset:17408
	ds_read_b128 v[192:195], v150 offset:18432
	ds_read_b128 v[196:199], v150 offset:19456
	ds_read_b128 v[200:203], v150 offset:20480
	ds_read_b128 v[204:207], v150 offset:21504
	ds_read_b128 v[208:211], v150 offset:22528
	ds_read_b128 v[212:215], v150 offset:23552
	global_load_lds_dwordx4 v[216:217], off
	s_add_i32 m0, s64, 0x2000
	s_add_u32 s64, s38, 0x40000
	v_lshl_add_u64 v[218:219], s[38:39], 0, v[136:137]
	s_addc_u32 s65, s39, 0
	s_add_i32 s66, s56, s47
	global_load_lds_dwordx4 v[218:219], off
	s_nop 0
	s_mov_b32 m0, s66
	v_lshl_add_u64 v[222:223], s[40:41], 0, v[134:135]
	global_load_lds_dwordx4 v132, s[64:65]
	s_nop 0
	s_add_i32 m0, s66, 0x2000
	s_nop 0
	global_load_lds_dwordx4 v136, s[64:65]
	v_lshl_add_u64 v[220:221], s[40:41], 0, v[130:131]
	s_mov_b32 m0, s25
	s_nop 0
	global_load_lds_dwordx4 v[220:221], off
	s_mov_b32 m0, s48
	s_nop 0
	global_load_lds_dwordx4 v[222:223], off
	s_waitcnt vmcnt(8)
	s_waitcnt lgkmcnt(0)
	s_barrier
	s_setprio 1
	s_waitcnt lgkmcnt(0)
	v_mfma_f32_16x16x32_bf16 v[62:65], v[152:155], v[184:187], v[62:65]
	v_mfma_f32_16x16x32_bf16 v[58:61], v[160:163], v[184:187], v[58:61]
	v_mfma_f32_16x16x32_bf16 v[54:57], v[152:155], v[192:195], v[54:57]
	v_mfma_f32_16x16x32_bf16 v[50:53], v[160:163], v[192:195], v[50:53]
	v_mfma_f32_16x16x32_bf16 v[38:41], v[152:155], v[200:203], v[38:41]
	v_mfma_f32_16x16x32_bf16 v[34:37], v[160:163], v[200:203], v[34:37]
	v_mfma_f32_16x16x32_bf16 v[22:25], v[152:155], v[208:211], v[22:25]
	v_mfma_f32_16x16x32_bf16 v[18:21], v[160:163], v[208:211], v[18:21]
	v_mfma_f32_16x16x32_bf16 v[62:65], v[156:159], v[188:191], v[62:65]
	v_mfma_f32_16x16x32_bf16 v[58:61], v[164:167], v[188:191], v[58:61]
	v_mfma_f32_16x16x32_bf16 v[54:57], v[156:159], v[196:199], v[54:57]
	v_mfma_f32_16x16x32_bf16 v[50:53], v[164:167], v[196:199], v[50:53]
	v_mfma_f32_16x16x32_bf16 v[38:41], v[156:159], v[204:207], v[38:41]
	v_mfma_f32_16x16x32_bf16 v[34:37], v[164:167], v[204:207], v[34:37]
	v_mfma_f32_16x16x32_bf16 v[22:25], v[156:159], v[212:215], v[22:25]
	v_mfma_f32_16x16x32_bf16 v[18:21], v[164:167], v[212:215], v[18:21]
	s_setprio 0
	s_setprio 1
	v_mfma_f32_16x16x32_bf16 v[46:49], v[168:171], v[184:187], v[46:49]
	v_mfma_f32_16x16x32_bf16 v[42:45], v[176:179], v[184:187], v[42:45]
	v_mfma_f32_16x16x32_bf16 v[30:33], v[168:171], v[192:195], v[30:33]
	v_mfma_f32_16x16x32_bf16 v[26:29], v[176:179], v[192:195], v[26:29]
	v_mfma_f32_16x16x32_bf16 v[14:17], v[168:171], v[200:203], v[14:17]
	v_mfma_f32_16x16x32_bf16 v[10:13], v[176:179], v[200:203], v[10:13]
	v_mfma_f32_16x16x32_bf16 v[6:9], v[168:171], v[208:211], v[6:9]
	v_mfma_f32_16x16x32_bf16 v[2:5], v[176:179], v[208:211], v[2:5]
	v_mfma_f32_16x16x32_bf16 v[46:49], v[172:175], v[188:191], v[46:49]
	v_mfma_f32_16x16x32_bf16 v[42:45], v[180:183], v[188:191], v[42:45]
	v_mfma_f32_16x16x32_bf16 v[30:33], v[172:175], v[196:199], v[30:33]
	v_mfma_f32_16x16x32_bf16 v[26:29], v[180:183], v[196:199], v[26:29]
	v_mfma_f32_16x16x32_bf16 v[14:17], v[172:175], v[204:207], v[14:17]
	v_mfma_f32_16x16x32_bf16 v[10:13], v[180:183], v[204:207], v[10:13]
	v_mfma_f32_16x16x32_bf16 v[6:9], v[172:175], v[212:215], v[6:9]
	v_mfma_f32_16x16x32_bf16 v[2:5], v[180:183], v[212:215], v[2:5]
	s_setprio 0
	s_barrier
	s_add_i32 s64, 0, 0x18000
	v_add_u32_e32 v151, s64, v146
	s_add_i32 s65, 0, 0x1c000
	ds_read_b128 v[152:155], v151
	ds_read_b128 v[156:159], v151 offset:1024
	ds_read_b128 v[160:163], v151 offset:2048
	ds_read_b128 v[164:167], v151 offset:3072
	v_add_u32_e32 v151, s65, v146
	ds_read_b128 v[168:171], v151
	ds_read_b128 v[172:175], v151 offset:1024
	ds_read_b128 v[176:179], v151 offset:2048
	ds_read_b128 v[180:183], v151 offset:3072
	s_add_u32 s40, s40, 0x40000
	s_addc_u32 s41, s41, 0
	s_mov_b32 m0, s49
	s_nop 0
	ds_read_b128 v[184:187], v150 offset:32768
	ds_read_b128 v[188:191], v150 offset:33792
	ds_read_b128 v[192:195], v150 offset:34816
	ds_read_b128 v[196:199], v150 offset:35840
	ds_read_b128 v[200:203], v150 offset:36864
	ds_read_b128 v[204:207], v150 offset:37888
	ds_read_b128 v[208:211], v150 offset:38912
	ds_read_b128 v[212:215], v150 offset:39936
	global_load_lds_dwordx4 v130, s[40:41]
	v_lshl_add_u64 v[224:225], s[40:41], 0, v[134:135]
	s_mov_b32 m0, s50
	s_nop 0
	global_load_lds_dwordx4 v[224:225], off
	s_waitcnt vmcnt(8)
	s_waitcnt lgkmcnt(0)
	s_barrier
	s_setprio 1
	s_waitcnt lgkmcnt(0)
	v_mfma_f32_16x16x32_bf16 v[126:129], v[152:155], v[184:187], v[126:129]
	v_mfma_f32_16x16x32_bf16 v[122:125], v[160:163], v[184:187], v[122:125]
	v_mfma_f32_16x16x32_bf16 v[118:121], v[152:155], v[192:195], v[118:121]
	v_mfma_f32_16x16x32_bf16 v[114:117], v[160:163], v[192:195], v[114:117]
	v_mfma_f32_16x16x32_bf16 v[102:105], v[152:155], v[200:203], v[102:105]
	v_mfma_f32_16x16x32_bf16 v[98:101], v[160:163], v[200:203], v[98:101]
	v_mfma_f32_16x16x32_bf16 v[86:89], v[152:155], v[208:211], v[86:89]
	v_mfma_f32_16x16x32_bf16 v[82:85], v[160:163], v[208:211], v[82:85]
	v_mfma_f32_16x16x32_bf16 v[126:129], v[156:159], v[188:191], v[126:129]
	v_mfma_f32_16x16x32_bf16 v[122:125], v[164:167], v[188:191], v[122:125]
	v_mfma_f32_16x16x32_bf16 v[118:121], v[156:159], v[196:199], v[118:121]
	v_mfma_f32_16x16x32_bf16 v[114:117], v[164:167], v[196:199], v[114:117]
	v_mfma_f32_16x16x32_bf16 v[102:105], v[156:159], v[204:207], v[102:105]
	v_mfma_f32_16x16x32_bf16 v[98:101], v[164:167], v[204:207], v[98:101]
	v_mfma_f32_16x16x32_bf16 v[86:89], v[156:159], v[212:215], v[86:89]
	v_mfma_f32_16x16x32_bf16 v[82:85], v[164:167], v[212:215], v[82:85]
	s_setprio 0
	s_setprio 1
	v_mfma_f32_16x16x32_bf16 v[110:113], v[168:171], v[184:187], v[110:113]
	v_mfma_f32_16x16x32_bf16 v[106:109], v[176:179], v[184:187], v[106:109]
	v_mfma_f32_16x16x32_bf16 v[94:97], v[168:171], v[192:195], v[94:97]
	v_mfma_f32_16x16x32_bf16 v[90:93], v[176:179], v[192:195], v[90:93]
	v_mfma_f32_16x16x32_bf16 v[78:81], v[168:171], v[200:203], v[78:81]
	v_mfma_f32_16x16x32_bf16 v[74:77], v[176:179], v[200:203], v[74:77]
	v_mfma_f32_16x16x32_bf16 v[70:73], v[168:171], v[208:211], v[70:73]
	v_mfma_f32_16x16x32_bf16 v[66:69], v[176:179], v[208:211], v[66:69]
	v_mfma_f32_16x16x32_bf16 v[110:113], v[172:175], v[188:191], v[110:113]
	v_mfma_f32_16x16x32_bf16 v[106:109], v[180:183], v[188:191], v[106:109]
	v_mfma_f32_16x16x32_bf16 v[94:97], v[172:175], v[196:199], v[94:97]
	v_mfma_f32_16x16x32_bf16 v[90:93], v[180:183], v[196:199], v[90:93]
	v_mfma_f32_16x16x32_bf16 v[78:81], v[172:175], v[204:207], v[78:81]
	v_mfma_f32_16x16x32_bf16 v[74:77], v[180:183], v[204:207], v[74:77]
	v_mfma_f32_16x16x32_bf16 v[70:73], v[172:175], v[212:215], v[70:73]
	v_mfma_f32_16x16x32_bf16 v[66:69], v[180:183], v[212:215], v[66:69]
	s_setprio 0
	s_barrier
	s_add_i32 s40, s64, s47
	v_lshl_add_u64 v[216:217], v[216:217], 0, s[12:13]
	s_mov_b32 m0, s40
	ds_read_b128 v[184:187], v150 offset:49152
	ds_read_b128 v[188:191], v150 offset:50176
	ds_read_b128 v[192:195], v150 offset:51200
	ds_read_b128 v[196:199], v150 offset:52224
	ds_read_b128 v[200:203], v150 offset:53248
	ds_read_b128 v[204:207], v150 offset:54272
	ds_read_b128 v[208:211], v150 offset:55296
	ds_read_b128 v[212:215], v150 offset:56320
	global_load_lds_dwordx4 v[216:217], off
	s_add_i32 m0, s40, 0x2000
	s_add_u32 s38, s38, 0x40080
	v_lshl_add_u64 v[216:217], v[218:219], 0, s[12:13]
	s_addc_u32 s39, s39, 0
	s_add_i32 s40, s65, s47
	global_load_lds_dwordx4 v[216:217], off
	s_nop 0
	s_mov_b32 m0, s40
	s_nop 0
	global_load_lds_dwordx4 v132, s[38:39]
	s_nop 0
	s_add_i32 m0, s40, 0x2000
	s_nop 0
	global_load_lds_dwordx4 v136, s[38:39]
	v_lshl_add_u64 v[216:217], v[220:221], 0, s[12:13]
	s_mov_b32 m0, s52
	s_nop 0
	global_load_lds_dwordx4 v[216:217], off
	v_lshl_add_u64 v[216:217], v[222:223], 0, s[12:13]
	s_mov_b32 m0, s53
	s_nop 0
	global_load_lds_dwordx4 v[216:217], off
	s_waitcnt vmcnt(8)
	s_waitcnt lgkmcnt(0)
	s_barrier
	s_setprio 1
	s_waitcnt lgkmcnt(0)
	v_mfma_f32_16x16x32_bf16 v[62:65], v[152:155], v[184:187], v[62:65]
	v_mfma_f32_16x16x32_bf16 v[58:61], v[160:163], v[184:187], v[58:61]
	v_mfma_f32_16x16x32_bf16 v[54:57], v[152:155], v[192:195], v[54:57]
	v_mfma_f32_16x16x32_bf16 v[50:53], v[160:163], v[192:195], v[50:53]
	v_mfma_f32_16x16x32_bf16 v[38:41], v[152:155], v[200:203], v[38:41]
	v_mfma_f32_16x16x32_bf16 v[34:37], v[160:163], v[200:203], v[34:37]
	v_mfma_f32_16x16x32_bf16 v[22:25], v[152:155], v[208:211], v[22:25]
	v_mfma_f32_16x16x32_bf16 v[18:21], v[160:163], v[208:211], v[18:21]
	v_mfma_f32_16x16x32_bf16 v[62:65], v[156:159], v[188:191], v[62:65]
	v_mfma_f32_16x16x32_bf16 v[58:61], v[164:167], v[188:191], v[58:61]
	v_mfma_f32_16x16x32_bf16 v[54:57], v[156:159], v[196:199], v[54:57]
	v_mfma_f32_16x16x32_bf16 v[50:53], v[164:167], v[196:199], v[50:53]
	v_mfma_f32_16x16x32_bf16 v[38:41], v[156:159], v[204:207], v[38:41]
	v_mfma_f32_16x16x32_bf16 v[34:37], v[164:167], v[204:207], v[34:37]
	v_mfma_f32_16x16x32_bf16 v[22:25], v[156:159], v[212:215], v[22:25]
	v_mfma_f32_16x16x32_bf16 v[18:21], v[164:167], v[212:215], v[18:21]
	s_setprio 0
	s_setprio 1
	v_mfma_f32_16x16x32_bf16 v[46:49], v[168:171], v[184:187], v[46:49]
	v_mfma_f32_16x16x32_bf16 v[42:45], v[176:179], v[184:187], v[42:45]
	v_mfma_f32_16x16x32_bf16 v[30:33], v[168:171], v[192:195], v[30:33]
	v_mfma_f32_16x16x32_bf16 v[26:29], v[176:179], v[192:195], v[26:29]
	v_mfma_f32_16x16x32_bf16 v[14:17], v[168:171], v[200:203], v[14:17]
	v_mfma_f32_16x16x32_bf16 v[10:13], v[176:179], v[200:203], v[10:13]
	v_mfma_f32_16x16x32_bf16 v[6:9], v[168:171], v[208:211], v[6:9]
	v_mfma_f32_16x16x32_bf16 v[2:5], v[176:179], v[208:211], v[2:5]
	v_mfma_f32_16x16x32_bf16 v[46:49], v[172:175], v[188:191], v[46:49]
	v_mfma_f32_16x16x32_bf16 v[42:45], v[180:183], v[188:191], v[42:45]
	v_mfma_f32_16x16x32_bf16 v[30:33], v[172:175], v[196:199], v[30:33]
	v_mfma_f32_16x16x32_bf16 v[26:29], v[180:183], v[196:199], v[26:29]
	v_mfma_f32_16x16x32_bf16 v[14:17], v[172:175], v[204:207], v[14:17]
	v_mfma_f32_16x16x32_bf16 v[10:13], v[180:183], v[204:207], v[10:13]
	v_mfma_f32_16x16x32_bf16 v[6:9], v[172:175], v[212:215], v[6:9]
	v_mfma_f32_16x16x32_bf16 v[2:5], v[180:183], v[212:215], v[2:5]
	s_setprio 0
	s_barrier
	s_add_i32 s63, s63, 2
	s_add_u32 s36, s36, 0x100
	s_addc_u32 s37, s37, 0
	s_add_u32 s29, s29, 0x100
	s_addc_u32 s62, s62, 0
	s_cmp_gt_u32 s63, 13
	s_cbranch_scc0 .LBB0_576
	s_and_b64 vcc, exec, s[14:15]
	s_cbranch_vccz .LBB0_579
	s_barrier

.LBB0_639:
	s_add_u32 s6, s2, 0xa900000
	s_addc_u32 s7, s3, 0
	s_lshl_b32 s2, s8, 5
	s_mov_b64 s[8:9], 0x80
	s_and_b32 s15, s2, 0x60
	s_add_i32 m0, s25, 0x18000
	v_lshl_add_u64 v[8:9], v[8:9], 0, s[8:9]
	s_lshl_b32 s14, s13, 13
	s_lshl_b32 s16, s15, 7
	s_waitcnt vmcnt(2)
	s_barrier
	global_load_lds_dwordx4 v[8:9], off
	v_lshl_add_u64 v[6:7], v[6:7], 0, s[8:9]
	s_add_i32 m0, s25, 0x1a000
	s_add_i32 s45, s25, 0x8000
	s_add_i32 s46, s25, 0xa000
	global_load_lds_dwordx4 v[6:7], off
	v_lshl_add_u64 v[2:3], v[2:3], 0, s[8:9]
	s_mov_b32 m0, s45
	s_add_u32 s2, s28, 0x40080
	global_load_lds_dwordx4 v[2:3], off
	v_lshl_add_u64 v[2:3], v[4:5], 0, s[8:9]
	s_mov_b32 m0, s46
	s_addc_u32 s3, s29, 0
	global_load_lds_dwordx4 v[2:3], off
	s_add_i32 m0, s25, 0x1c000
	s_nop 0
	global_load_lds_dwordx4 v134, s[2:3]
	s_nop 0
	s_add_i32 m0, s25, 0x1e000
	v_lshlrev_b32_e32 v4, 2, v10
	global_load_lds_dwordx4 v130, s[2:3]
	v_and_b32_e32 v2, 15, v10
	v_lshlrev_b32_e32 v3, 1, v14
	v_lshlrev_b32_e32 v5, 6, v10
	s_movk_i32 s2, 0x3c0
	v_lshl_or_b32 v1, s13, 6, v2
	v_lshl_or_b32 v2, v2, 6, v3
	v_and_b32_e32 v4, 32, v4
	v_and_or_b32 v3, v5, s2, v3
	v_bitop3_b32 v148, s16, v3, v4 bitop3:0xf6
	v_lshlrev_b32_e32 v3, 8, v10
	v_bitop3_b32 v2, v2, s14, v4 bitop3:0xde
	v_and_b32_e32 v3, 0x38000, v3
	v_lshlrev_b32_e32 v4, 11, v15
	v_or3_b32 v3, v12, v3, v4
	s_waitcnt vmcnt(0)
	v_add_u32_e32 v138, v3, v13
	v_lshlrev_b32_e32 v3, 4, v11
	s_waitcnt vmcnt(6)
	s_cmpk_lt_u32 s10, 0x100
	v_and_b32_e32 v3, 0x78000, v3
	s_sext_i32_i8 s51, s12
	s_cselect_b64 s[12:13], -1, 0
	v_or3_b32 v3, v12, v3, v4
	s_add_i32 s48, 0, 0x10000
	s_add_i32 s49, 0, 0x14000
	s_ashr_i32 s47, s11, 31
	v_or_b32_e32 v149, s15, v14
	v_mov_b32_e32 v139, v135
	v_add_u32_e32 v140, v3, v13
	v_mov_b32_e32 v141, v135
	v_mov_b64_e32 v[142:143], 0xb00
	v_mov_b64_e32 v[144:145], 0xaff
	v_add_u32_e32 v150, s48, v148
	v_add_u32_e32 v151, s49, v148
	v_add_u32_e32 v152, 0, v2
	s_movk_i32 s50, 0x1600
	s_barrier
	s_branch .LBB0_642

.LBB0_645:
	ds_read_b128 v[154:157], v150
	ds_read_b128 v[158:161], v150 offset:1024
	ds_read_b128 v[162:165], v150 offset:2048
	ds_read_b128 v[166:169], v150 offset:3072
	ds_read_b128 v[170:173], v151
	ds_read_b128 v[174:177], v151 offset:1024
	ds_read_b128 v[178:181], v151 offset:2048
	ds_read_b128 v[182:185], v151 offset:3072
	s_add_u32 s28, s26, 0xfffc0080
	s_addc_u32 s29, s27, -1
	s_cmp_eq_u32 s53, 12
	s_cselect_b32 s31, s10, s29
	s_cselect_b32 s30, s17, s28
	s_cselect_b32 s29, s15, s52
	s_cselect_b32 s28, s20, s21
	s_nop 0
	s_add_i32 m0, s25, 0xc000
	ds_read_b128 v[186:189], v152
	ds_read_b128 v[190:193], v152 offset:1024
	ds_read_b128 v[194:197], v152 offset:2048
	ds_read_b128 v[198:201], v152 offset:3072
	ds_read_b128 v[202:205], v152 offset:4096
	ds_read_b128 v[206:209], v152 offset:5120
	ds_read_b128 v[210:213], v152 offset:6144
	ds_read_b128 v[214:217], v152 offset:7168
	global_load_lds_dwordx4 v138, s[26:27]
	s_nop 0
	s_add_i32 m0, s25, 0xe000
	s_nop 0
	global_load_lds_dwordx4 v140, s[26:27]
	s_waitcnt vmcnt(8)
	s_waitcnt lgkmcnt(0)
	s_barrier
	s_setprio 1
	s_waitcnt lgkmcnt(0)
	v_mfma_f32_16x16x32_bf16 v[126:129], v[154:157], v[186:189], v[126:129]
	v_mfma_f32_16x16x32_bf16 v[122:125], v[162:165], v[186:189], v[122:125]
	v_mfma_f32_16x16x32_bf16 v[110:113], v[154:157], v[194:197], v[110:113]
	v_mfma_f32_16x16x32_bf16 v[106:109], v[162:165], v[194:197], v[106:109]
	v_mfma_f32_16x16x32_bf16 v[94:97], v[154:157], v[202:205], v[94:97]
	v_mfma_f32_16x16x32_bf16 v[90:93], v[162:165], v[202:205], v[90:93]
	v_mfma_f32_16x16x32_bf16 v[78:81], v[154:157], v[210:213], v[78:81]
	v_mfma_f32_16x16x32_bf16 v[74:77], v[162:165], v[210:213], v[74:77]
	v_mfma_f32_16x16x32_bf16 v[126:129], v[158:161], v[190:193], v[126:129]
	v_mfma_f32_16x16x32_bf16 v[122:125], v[166:169], v[190:193], v[122:125]
	v_mfma_f32_16x16x32_bf16 v[110:113], v[158:161], v[198:201], v[110:113]
	v_mfma_f32_16x16x32_bf16 v[106:109], v[166:169], v[198:201], v[106:109]
	v_mfma_f32_16x16x32_bf16 v[94:97], v[158:161], v[206:209], v[94:97]
	v_mfma_f32_16x16x32_bf16 v[90:93], v[166:169], v[206:209], v[90:93]
	v_mfma_f32_16x16x32_bf16 v[78:81], v[158:161], v[214:217], v[78:81]
	v_mfma_f32_16x16x32_bf16 v[74:77], v[166:169], v[214:217], v[74:77]
	s_setprio 0
	s_setprio 1
	v_mfma_f32_16x16x32_bf16 v[118:121], v[170:173], v[186:189], v[118:121]
	v_mfma_f32_16x16x32_bf16 v[114:117], v[178:181], v[186:189], v[114:117]
	v_mfma_f32_16x16x32_bf16 v[102:105], v[170:173], v[194:197], v[102:105]
	v_mfma_f32_16x16x32_bf16 v[98:101], v[178:181], v[194:197], v[98:101]
	v_mfma_f32_16x16x32_bf16 v[86:89], v[170:173], v[202:205], v[86:89]
	v_mfma_f32_16x16x32_bf16 v[82:85], v[178:181], v[202:205], v[82:85]
	v_mfma_f32_16x16x32_bf16 v[70:73], v[170:173], v[210:213], v[70:73]
	v_mfma_f32_16x16x32_bf16 v[66:69], v[178:181], v[210:213], v[66:69]
	v_mfma_f32_16x16x32_bf16 v[118:121], v[174:177], v[190:193], v[118:121]
	v_mfma_f32_16x16x32_bf16 v[114:117], v[182:185], v[190:193], v[114:117]
	v_mfma_f32_16x16x32_bf16 v[102:105], v[174:177], v[198:201], v[102:105]
	v_mfma_f32_16x16x32_bf16 v[98:101], v[182:185], v[198:201], v[98:101]
	v_mfma_f32_16x16x32_bf16 v[86:89], v[174:177], v[206:209], v[86:89]
	v_mfma_f32_16x16x32_bf16 v[82:85], v[182:185], v[206:209], v[82:85]
	v_mfma_f32_16x16x32_bf16 v[70:73], v[174:177], v[214:217], v[70:73]
	v_mfma_f32_16x16x32_bf16 v[66:69], v[182:185], v[214:217], v[66:69]
	s_setprio 0
	s_barrier
	s_add_i32 s54, s48, s38
	v_lshl_add_u64 v[146:147], s[28:29], 0, v[134:135]
	s_mov_b32 m0, s54
	ds_read_b128 v[186:189], v152 offset:16384
	ds_read_b128 v[190:193], v152 offset:17408
	ds_read_b128 v[194:197], v152 offset:18432
	ds_read_b128 v[198:201], v152 offset:19456
	ds_read_b128 v[202:205], v152 offset:20480
	ds_read_b128 v[206:209], v152 offset:21504
	ds_read_b128 v[210:213], v152 offset:22528
	ds_read_b128 v[214:217], v152 offset:23552
	global_load_lds_dwordx4 v[146:147], off
	s_add_i32 m0, s54, 0x2000
	s_add_u32 s54, s28, 0x40000
	v_lshl_add_u64 v[218:219], s[28:29], 0, v[130:131]
	s_addc_u32 s55, s29, 0
	s_add_i32 s56, s49, s38
	global_load_lds_dwordx4 v[218:219], off
	s_nop 0
	s_mov_b32 m0, s56
	v_lshl_add_u64 v[222:223], s[30:31], 0, v[132:133]
	global_load_lds_dwordx4 v134, s[54:55]
	s_nop 0
	s_add_i32 m0, s56, 0x2000
	s_nop 0
	global_load_lds_dwordx4 v130, s[54:55]
	v_lshl_add_u64 v[220:221], s[30:31], 0, v[136:137]
	s_mov_b32 m0, s25
	s_nop 0
	global_load_lds_dwordx4 v[220:221], off
	s_mov_b32 m0, s41
	s_nop 0
	global_load_lds_dwordx4 v[222:223], off
	s_waitcnt vmcnt(8)
	s_waitcnt lgkmcnt(0)
	s_barrier
	s_setprio 1
	s_waitcnt lgkmcnt(0)
	v_mfma_f32_16x16x32_bf16 v[62:65], v[154:157], v[186:189], v[62:65]
	v_mfma_f32_16x16x32_bf16 v[58:61], v[162:165], v[186:189], v[58:61]
	v_mfma_f32_16x16x32_bf16 v[46:49], v[154:157], v[194:197], v[46:49]
	v_mfma_f32_16x16x32_bf16 v[42:45], v[162:165], v[194:197], v[42:45]
	v_mfma_f32_16x16x32_bf16 v[30:33], v[154:157], v[202:205], v[30:33]
	v_mfma_f32_16x16x32_bf16 v[26:29], v[162:165], v[202:205], v[26:29]
	v_mfma_f32_16x16x32_bf16 v[14:17], v[154:157], v[210:213], v[14:17]
	v_mfma_f32_16x16x32_bf16 v[10:13], v[162:165], v[210:213], v[10:13]
	v_mfma_f32_16x16x32_bf16 v[62:65], v[158:161], v[190:193], v[62:65]
	v_mfma_f32_16x16x32_bf16 v[58:61], v[166:169], v[190:193], v[58:61]
	v_mfma_f32_16x16x32_bf16 v[46:49], v[158:161], v[198:201], v[46:49]
	v_mfma_f32_16x16x32_bf16 v[42:45], v[166:169], v[198:201], v[42:45]
	v_mfma_f32_16x16x32_bf16 v[30:33], v[158:161], v[206:209], v[30:33]
	v_mfma_f32_16x16x32_bf16 v[26:29], v[166:169], v[206:209], v[26:29]
	v_mfma_f32_16x16x32_bf16 v[14:17], v[158:161], v[214:217], v[14:17]
	v_mfma_f32_16x16x32_bf16 v[10:13], v[166:169], v[214:217], v[10:13]
	s_setprio 0
	s_setprio 1
	v_mfma_f32_16x16x32_bf16 v[54:57], v[170:173], v[186:189], v[54:57]
	v_mfma_f32_16x16x32_bf16 v[50:53], v[178:181], v[186:189], v[50:53]
	v_mfma_f32_16x16x32_bf16 v[38:41], v[170:173], v[194:197], v[38:41]
	v_mfma_f32_16x16x32_bf16 v[34:37], v[178:181], v[194:197], v[34:37]
	v_mfma_f32_16x16x32_bf16 v[22:25], v[170:173], v[202:205], v[22:25]
	v_mfma_f32_16x16x32_bf16 v[18:21], v[178:181], v[202:205], v[18:21]
	v_mfma_f32_16x16x32_bf16 v[6:9], v[170:173], v[210:213], v[6:9]
	v_mfma_f32_16x16x32_bf16 v[2:5], v[178:181], v[210:213], v[2:5]
	v_mfma_f32_16x16x32_bf16 v[54:57], v[174:177], v[190:193], v[54:57]
	v_mfma_f32_16x16x32_bf16 v[50:53], v[182:185], v[190:193], v[50:53]
	v_mfma_f32_16x16x32_bf16 v[38:41], v[174:177], v[198:201], v[38:41]
	v_mfma_f32_16x16x32_bf16 v[34:37], v[182:185], v[198:201], v[34:37]
	v_mfma_f32_16x16x32_bf16 v[22:25], v[174:177], v[206:209], v[22:25]
	v_mfma_f32_16x16x32_bf16 v[18:21], v[182:185], v[206:209], v[18:21]
	v_mfma_f32_16x16x32_bf16 v[6:9], v[174:177], v[214:217], v[6:9]
	v_mfma_f32_16x16x32_bf16 v[2:5], v[182:185], v[214:217], v[2:5]
	s_setprio 0
	s_barrier
	s_add_i32 s54, 0, 0x18000
	v_add_u32_e32 v153, s54, v148
	s_add_i32 s55, 0, 0x1c000
	ds_read_b128 v[154:157], v153
	ds_read_b128 v[158:161], v153 offset:1024
	ds_read_b128 v[162:165], v153 offset:2048
	ds_read_b128 v[166:169], v153 offset:3072
	v_add_u32_e32 v153, s55, v148
	ds_read_b128 v[170:173], v153
	ds_read_b128 v[174:177], v153 offset:1024
	ds_read_b128 v[178:181], v153 offset:2048
	ds_read_b128 v[182:185], v153 offset:3072
	s_add_u32 s30, s30, 0x40000
	s_addc_u32 s31, s31, 0
	s_mov_b32 m0, s42
	s_nop 0
	ds_read_b128 v[186:189], v152 offset:32768
	ds_read_b128 v[190:193], v152 offset:33792
	ds_read_b128 v[194:197], v152 offset:34816
	ds_read_b128 v[198:201], v152 offset:35840
	ds_read_b128 v[202:205], v152 offset:36864
	ds_read_b128 v[206:209], v152 offset:37888
	ds_read_b128 v[210:213], v152 offset:38912
	ds_read_b128 v[214:217], v152 offset:39936
	global_load_lds_dwordx4 v136, s[30:31]
	v_lshl_add_u64 v[224:225], s[30:31], 0, v[132:133]
	s_mov_b32 m0, s43
	s_nop 0
	global_load_lds_dwordx4 v[224:225], off
	s_waitcnt vmcnt(8)
	s_waitcnt lgkmcnt(0)
	s_barrier
	s_setprio 1
	s_waitcnt lgkmcnt(0)
	v_mfma_f32_16x16x32_bf16 v[126:129], v[154:157], v[186:189], v[126:129]
	v_mfma_f32_16x16x32_bf16 v[122:125], v[162:165], v[186:189], v[122:125]
	v_mfma_f32_16x16x32_bf16 v[110:113], v[154:157], v[194:197], v[110:113]
	v_mfma_f32_16x16x32_bf16 v[106:109], v[162:165], v[194:197], v[106:109]
	v_mfma_f32_16x16x32_bf16 v[94:97], v[154:157], v[202:205], v[94:97]
	v_mfma_f32_16x16x32_bf16 v[90:93], v[162:165], v[202:205], v[90:93]
	v_mfma_f32_16x16x32_bf16 v[78:81], v[154:157], v[210:213], v[78:81]
	v_mfma_f32_16x16x32_bf16 v[74:77], v[162:165], v[210:213], v[74:77]
	v_mfma_f32_16x16x32_bf16 v[126:129], v[158:161], v[190:193], v[126:129]
	v_mfma_f32_16x16x32_bf16 v[122:125], v[166:169], v[190:193], v[122:125]
	v_mfma_f32_16x16x32_bf16 v[110:113], v[158:161], v[198:201], v[110:113]
	v_mfma_f32_16x16x32_bf16 v[106:109], v[166:169], v[198:201], v[106:109]
	v_mfma_f32_16x16x32_bf16 v[94:97], v[158:161], v[206:209], v[94:97]
	v_mfma_f32_16x16x32_bf16 v[90:93], v[166:169], v[206:209], v[90:93]
	v_mfma_f32_16x16x32_bf16 v[78:81], v[158:161], v[214:217], v[78:81]
	v_mfma_f32_16x16x32_bf16 v[74:77], v[166:169], v[214:217], v[74:77]
	s_setprio 0
	s_setprio 1
	v_mfma_f32_16x16x32_bf16 v[118:121], v[170:173], v[186:189], v[118:121]
	v_mfma_f32_16x16x32_bf16 v[114:117], v[178:181], v[186:189], v[114:117]
	v_mfma_f32_16x16x32_bf16 v[102:105], v[170:173], v[194:197], v[102:105]
	v_mfma_f32_16x16x32_bf16 v[98:101], v[178:181], v[194:197], v[98:101]
	v_mfma_f32_16x16x32_bf16 v[86:89], v[170:173], v[202:205], v[86:89]
	v_mfma_f32_16x16x32_bf16 v[82:85], v[178:181], v[202:205], v[82:85]
	v_mfma_f32_16x16x32_bf16 v[70:73], v[170:173], v[210:213], v[70:73]
	v_mfma_f32_16x16x32_bf16 v[66:69], v[178:181], v[210:213], v[66:69]
	v_mfma_f32_16x16x32_bf16 v[118:121], v[174:177], v[190:193], v[118:121]
	v_mfma_f32_16x16x32_bf16 v[114:117], v[182:185], v[190:193], v[114:117]
	v_mfma_f32_16x16x32_bf16 v[102:105], v[174:177], v[198:201], v[102:105]
	v_mfma_f32_16x16x32_bf16 v[98:101], v[182:185], v[198:201], v[98:101]
	v_mfma_f32_16x16x32_bf16 v[86:89], v[174:177], v[206:209], v[86:89]
	v_mfma_f32_16x16x32_bf16 v[82:85], v[182:185], v[206:209], v[82:85]
	v_mfma_f32_16x16x32_bf16 v[70:73], v[174:177], v[214:217], v[70:73]
	v_mfma_f32_16x16x32_bf16 v[66:69], v[182:185], v[214:217], v[66:69]
	s_setprio 0
	s_barrier
	s_add_i32 s30, s54, s38
	v_lshl_add_u64 v[146:147], v[146:147], 0, s[8:9]
	s_mov_b32 m0, s30
	ds_read_b128 v[186:189], v152 offset:49152
	ds_read_b128 v[190:193], v152 offset:50176
	ds_read_b128 v[194:197], v152 offset:51200
	ds_read_b128 v[198:201], v152 offset:52224
	ds_read_b128 v[202:205], v152 offset:53248
	ds_read_b128 v[206:209], v152 offset:54272
	ds_read_b128 v[210:213], v152 offset:55296
	ds_read_b128 v[214:217], v152 offset:56320
	global_load_lds_dwordx4 v[146:147], off
	s_add_i32 m0, s30, 0x2000
	s_add_u32 s28, s28, 0x40080
	v_lshl_add_u64 v[146:147], v[218:219], 0, s[8:9]
	s_addc_u32 s29, s29, 0
	s_add_i32 s30, s55, s38
	global_load_lds_dwordx4 v[146:147], off
	s_nop 0
	s_mov_b32 m0, s30
	s_nop 0
	global_load_lds_dwordx4 v134, s[28:29]
	s_nop 0
	s_add_i32 m0, s30, 0x2000
	s_nop 0
	global_load_lds_dwordx4 v130, s[28:29]
	v_lshl_add_u64 v[146:147], v[220:221], 0, s[8:9]
	s_mov_b32 m0, s45
	s_nop 0
	global_load_lds_dwordx4 v[146:147], off
	v_lshl_add_u64 v[146:147], v[222:223], 0, s[8:9]
	s_mov_b32 m0, s46
	s_nop 0
	global_load_lds_dwordx4 v[146:147], off
	s_waitcnt vmcnt(8)
	s_waitcnt lgkmcnt(0)
	s_barrier
	s_setprio 1
	s_waitcnt lgkmcnt(0)
	v_mfma_f32_16x16x32_bf16 v[62:65], v[154:157], v[186:189], v[62:65]
	v_mfma_f32_16x16x32_bf16 v[58:61], v[162:165], v[186:189], v[58:61]
	v_mfma_f32_16x16x32_bf16 v[46:49], v[154:157], v[194:197], v[46:49]
	v_mfma_f32_16x16x32_bf16 v[42:45], v[162:165], v[194:197], v[42:45]
	v_mfma_f32_16x16x32_bf16 v[30:33], v[154:157], v[202:205], v[30:33]
	v_mfma_f32_16x16x32_bf16 v[26:29], v[162:165], v[202:205], v[26:29]
	v_mfma_f32_16x16x32_bf16 v[14:17], v[154:157], v[210:213], v[14:17]
	v_mfma_f32_16x16x32_bf16 v[10:13], v[162:165], v[210:213], v[10:13]
	v_mfma_f32_16x16x32_bf16 v[62:65], v[158:161], v[190:193], v[62:65]
	v_mfma_f32_16x16x32_bf16 v[58:61], v[166:169], v[190:193], v[58:61]
	v_mfma_f32_16x16x32_bf16 v[46:49], v[158:161], v[198:201], v[46:49]
	v_mfma_f32_16x16x32_bf16 v[42:45], v[166:169], v[198:201], v[42:45]
	v_mfma_f32_16x16x32_bf16 v[30:33], v[158:161], v[206:209], v[30:33]
	v_mfma_f32_16x16x32_bf16 v[26:29], v[166:169], v[206:209], v[26:29]
	v_mfma_f32_16x16x32_bf16 v[14:17], v[158:161], v[214:217], v[14:17]
	v_mfma_f32_16x16x32_bf16 v[10:13], v[166:169], v[214:217], v[10:13]
	s_setprio 0
	s_setprio 1
	v_mfma_f32_16x16x32_bf16 v[54:57], v[170:173], v[186:189], v[54:57]
	v_mfma_f32_16x16x32_bf16 v[50:53], v[178:181], v[186:189], v[50:53]
	v_mfma_f32_16x16x32_bf16 v[38:41], v[170:173], v[194:197], v[38:41]
	v_mfma_f32_16x16x32_bf16 v[34:37], v[178:181], v[194:197], v[34:37]
	v_mfma_f32_16x16x32_bf16 v[22:25], v[170:173], v[202:205], v[22:25]
	v_mfma_f32_16x16x32_bf16 v[18:21], v[178:181], v[202:205], v[18:21]
	v_mfma_f32_16x16x32_bf16 v[6:9], v[170:173], v[210:213], v[6:9]
	v_mfma_f32_16x16x32_bf16 v[2:5], v[178:181], v[210:213], v[2:5]
	v_mfma_f32_16x16x32_bf16 v[54:57], v[174:177], v[190:193], v[54:57]
	v_mfma_f32_16x16x32_bf16 v[50:53], v[182:185], v[190:193], v[50:53]
	v_mfma_f32_16x16x32_bf16 v[38:41], v[174:177], v[198:201], v[38:41]
	v_mfma_f32_16x16x32_bf16 v[34:37], v[182:185], v[198:201], v[34:37]
	v_mfma_f32_16x16x32_bf16 v[22:25], v[174:177], v[206:209], v[22:25]
	v_mfma_f32_16x16x32_bf16 v[18:21], v[182:185], v[206:209], v[18:21]
	v_mfma_f32_16x16x32_bf16 v[6:9], v[174:177], v[214:217], v[6:9]
	v_mfma_f32_16x16x32_bf16 v[2:5], v[182:185], v[214:217], v[2:5]
	s_setprio 0
	s_barrier
	s_add_i32 s53, s53, 2
	s_add_u32 s26, s26, 0x100
	s_addc_u32 s27, s27, 0
	s_add_u32 s21, s21, 0x100
	s_addc_u32 s52, s52, 0
	s_cmp_gt_u32 s53, 13
	s_cbranch_scc0 .LBB0_645
	s_and_b64 vcc, exec, s[12:13]
	s_cbranch_vccz .LBB0_648
	s_barrier

.LBB0_683:
	s_add_u32 s8, s2, 0x6900000
	s_addc_u32 s9, s3, 0
	s_lshl_b32 s2, s5, 5
	s_mov_b64 s[12:13], 0x80
	s_and_b32 s5, s2, 0x60
	s_add_i32 m0, s42, 0x18000
	v_lshl_add_u64 v[8:9], v[8:9], 0, s[12:13]
	s_lshl_b32 s15, s4, 13
	s_lshl_b32 s16, s5, 7
	s_waitcnt vmcnt(2)
	s_barrier
	global_load_lds_dwordx4 v[8:9], off
	v_lshl_add_u64 v[6:7], v[6:7], 0, s[12:13]
	s_add_i32 m0, s42, 0x1a000
	s_add_i32 s47, s42, 0x8000
	s_add_i32 s48, s42, 0xa000
	global_load_lds_dwordx4 v[6:7], off
	v_lshl_add_u64 v[2:3], v[2:3], 0, s[12:13]
	s_mov_b32 m0, s47
	s_add_u32 s2, s30, 0xb0080
	global_load_lds_dwordx4 v[2:3], off
	v_lshl_add_u64 v[2:3], v[4:5], 0, s[12:13]
	s_mov_b32 m0, s48
	s_addc_u32 s3, s31, 0
	global_load_lds_dwordx4 v[2:3], off
	s_add_i32 m0, s42, 0x1c000
	s_nop 0
	global_load_lds_dwordx4 v132, s[2:3]
	s_nop 0
	s_add_i32 m0, s42, 0x1e000
	v_lshlrev_b32_e32 v4, 2, v10
	global_load_lds_dwordx4 v136, s[2:3]
	v_and_b32_e32 v2, 15, v10
	v_lshlrev_b32_e32 v3, 1, v13
	v_lshlrev_b32_e32 v5, 6, v10
	s_movk_i32 s2, 0x3c0
	v_lshl_or_b32 v1, s4, 6, v2
	v_lshl_or_b32 v2, v2, 6, v3
	v_and_b32_e32 v4, 32, v4
	v_and_or_b32 v3, v5, s2, v3
	v_bitop3_b32 v146, s16, v3, v4 bitop3:0xf6
	s_waitcnt vmcnt(6)
	s_cmpk_lt_u32 s10, 0x100
	v_add_u16_e32 v3, v11, v12
	s_sext_i32_i8 s59, s14
	v_bitop3_b32 v2, v2, s15, v4 bitop3:0xde
	s_cselect_b64 s[14:15], -1, 0
	v_lshrrev_b16_e32 v3, 1, v3
	s_add_i32 s50, 0, 0x10000
	s_add_i32 s51, 0, 0x14000
	s_ashr_i32 s49, s11, 31
	v_or_b32_e32 v147, s5, v13
	s_waitcnt vmcnt(0)
	v_add_lshl_u32 v138, v14, v3, 1
	v_mov_b32_e32 v139, v133
	v_add_lshl_u32 v140, v15, v3, 1
	v_mov_b32_e32 v141, v133
	v_mov_b64_e32 v[142:143], 0x200
	v_mov_b64_e32 v[144:145], 0x1ff
	v_add_u32_e32 v148, s50, v146
	v_add_u32_e32 v149, s51, v146
	v_add_u32_e32 v150, 0, v2
	s_mov_b64 s[16:17], 0x40000
	s_mov_b32 s52, 0x40000
	s_mov_b64 s[18:19], 0x48000
	s_mov_b32 s53, 0x48000
	s_mov_b64 s[22:23], 0x50000
	s_mov_b32 s54, 0x50000
	s_mov_b64 s[24:25], 0x58000
	s_mov_b32 s55, 0x58000
	s_barrier
	s_branch .LBB0_686
